# RWKV forward substitution in 16-row blocks: in-block DPP f32 FMAs, between-block products on f32 matrix cores (v_mfma_f32_16x16x4_f32), permlane16/32_swap layout transposes (on s3m+rev5+prioB+s5c+glu)
# speedup vs baseline: 1.0060x; 1.0042x over previous
.LBB0_2331:
	s_nop 1
	ds_read_b128 v[2:5], v180 offset:36864
	v_add_u32_e32 v90, v112, v111
	ds_read_b128 v[6:9], v90
	ds_read_b128 v[92:95], v180 offset:9216
	ds_read_b128 v[18:21], v90 offset:36864
	ds_read_b128 v[34:37], v180
	ds_read_b128 v[96:99], v90 offset:18432
	ds_read_b128 v[100:103], v180 offset:36896
	ds_read_b128 v[184:187], v90 offset:32
	s_waitcnt lgkmcnt(4)
	v_mfma_f32_32x32x16_bf16 v[18:33], v[92:95], v[18:21], 0
	v_mfma_f32_32x32x16_bf16 v[2:17], v[2:5], v[6:9], 0
	s_waitcnt lgkmcnt(0)
	v_mfma_f32_32x32x16_bf16 v[2:17], v[100:103], v[184:187], v[2:17]
	ds_read_b128 v[100:103], v180 offset:9248
	ds_read_b128 v[184:187], v90 offset:36896
	v_mfma_f32_32x32x16_bf16 v[34:49], v[34:37], v[96:99], 0
	s_waitcnt lgkmcnt(0)
	v_mfma_f32_32x32x16_bf16 v[18:33], v[100:103], v[184:187], v[18:33]
	ds_read_b128 v[184:187], v180 offset:32
	ds_read_b128 v[196:199], v90 offset:18464
	s_waitcnt lgkmcnt(0)
	v_mfma_f32_32x32x16_bf16 v[34:49], v[184:187], v[196:199], v[34:49]
	ds_read_b128 v[184:187], v180 offset:36928
	ds_read_b128 v[200:203], v90 offset:64
	s_waitcnt lgkmcnt(0)
	v_mfma_f32_32x32x16_bf16 v[2:17], v[184:187], v[200:203], v[2:17]
	ds_read_b128 v[186:189], v180 offset:9280
	ds_read_b128 v[200:203], v90 offset:36928
	v_add_u32_e32 v184, 0x6800, v182
	s_waitcnt lgkmcnt(0)
	v_mfma_f32_32x32x16_bf16 v[18:33], v[186:189], v[200:203], v[18:33]
	ds_read_b128 v[200:203], v180 offset:64
	ds_read_b128 v[204:207], v90 offset:18496
	s_waitcnt lgkmcnt(0)
	v_mfma_f32_32x32x16_bf16 v[34:49], v[200:203], v[204:207], v[34:49]
	ds_read_b128 v[200:203], v180 offset:36960
	ds_read_b128 v[208:211], v90 offset:96
	s_waitcnt lgkmcnt(0)
	v_mfma_f32_32x32x16_bf16 v[2:17], v[200:203], v[208:211], v[2:17]
	ds_read_b128 v[200:203], v180 offset:9312
	ds_read_b128 v[208:211], v90 offset:36960
	s_waitcnt lgkmcnt(0)
	v_mfma_f32_32x32x16_bf16 v[18:33], v[200:203], v[208:211], v[18:33]
	ds_read_b128 v[208:211], v180 offset:96
	ds_read_b128 v[212:215], v90 offset:18528
	s_nop 5
	v_cndmask_b32_e64 v2, 0, v2, s[50:51]
	v_cndmask_b32_e64 v3, v3, 0, s[52:53]
	ds_write2_b32 v181, v2, v3 offset1:68
	v_cndmask_b32_e64 v3, 0, v4, s[56:57]
	v_cndmask_b32_e64 v4, 0, v5, s[60:61]
	v_cndmask_b32_e64 v5, 0, v6, s[64:65]
	ds_write_b32 v165, v3 offset:55296
	ds_write_b32 v166, v4 offset:55296
	ds_write_b32 v167, v5 offset:55296
	v_cndmask_b32_e64 v5, 0, v7, s[68:69]
	ds_write_b32 v168, v5 offset:55296
	v_cndmask_b32_e64 v5, 0, v8, s[72:73]
	ds_write_b32 v169, v5 offset:55296
	v_cndmask_b32_e64 v5, 0, v9, s[76:77]
	s_waitcnt lgkmcnt(6)
	v_mfma_f32_32x32x16_bf16 v[34:49], v[208:211], v[212:215], v[34:49]
	ds_write_b32 v170, v5 offset:55296
	v_cndmask_b32_e64 v5, 0, v10, s[80:81]
	ds_write_b32 v171, v5 offset:55296
	v_cndmask_b32_e64 v5, 0, v11, s[84:85]
	ds_write_b32 v172, v5 offset:55296
	v_cndmask_b32_e64 v5, 0, v12, s[88:89]
	ds_write_b32 v173, v5 offset:55296
	v_cndmask_b32_e64 v5, 0, v13, s[92:93]
	ds_write_b32 v174, v5 offset:55296
	v_cndmask_b32_e64 v5, 0, v14, s[96:97]
	ds_write_b32 v175, v5 offset:55296
	v_cndmask_b32_e64 v5, 0, v15, s[6:7]
	v_cndmask_b32_e64 v18, 0, v18, s[52:53]
	v_cndmask_b32_e64 v2, 0, v19, s[54:55]
	v_cndmask_b32_e64 v3, 0, v20, s[58:59]
	v_cndmask_b32_e64 v4, 0, v21, s[62:63]
	v_cndmask_b32_e64 v20, 0, v22, s[66:67]
	v_cndmask_b32_e64 v21, 0, v23, s[70:71]
	v_cndmask_b32_e64 v24, 0, v24, s[74:75]
	v_cndmask_b32_e64 v25, 0, v25, s[78:79]
	ds_write_b32 v176, v5 offset:55296
	v_cndmask_b32_e64 v5, 0, v16, s[10:11]
	v_cndmask_b32_e64 v26, 0, v26, s[82:83]
	v_cndmask_b32_e64 v27, 0, v27, s[86:87]
	v_cndmask_b32_e64 v28, 0, v28, s[90:91]
	v_cndmask_b32_e64 v29, 0, v29, s[94:95]
	v_cndmask_b32_e64 v30, 0, v30, s[4:5]
	v_cndmask_b32_e64 v31, 0, v31, s[8:9]
	ds_write_b32 v177, v5 offset:55296
	v_cndmask_b32_e64 v32, 0, v32, s[12:13]
	v_cndmask_b32_e64 v5, 0, v17, s[14:15]
	v_cndmask_b32_e64 v33, 0, v33, s[16:17]
	v_cvt_pk_bf16_f32 v18, v18, v2
	v_cvt_pk_bf16_f32 v19, v3, v4
	v_cvt_pk_bf16_f32 v20, v20, v21
	v_cvt_pk_bf16_f32 v21, v24, v25
	v_add_u32_e32 v24, 0xb000, v182
	v_cndmask_b32_e64 v34, v34, 0, s[50:51]
	v_cndmask_b32_e64 v35, 0, v35, s[52:53]
	v_cndmask_b32_e64 v36, v36, 0, s[56:57]
	v_cndmask_b32_e64 v37, v37, 0, s[60:61]
	v_cndmask_b32_e64 v22, v38, 0, s[64:65]
	v_cndmask_b32_e64 v23, v39, 0, s[68:69]
	v_cndmask_b32_e64 v38, v40, 0, s[72:73]
	v_cndmask_b32_e64 v39, v41, 0, s[76:77]
	ds_write_b32 v178, v5 offset:55296
	ds_write2_b64 v24, v[18:19], v[20:21] offset0:128 offset1:130
	v_cvt_pk_bf16_f32 v18, v26, v27
	v_cvt_pk_bf16_f32 v19, v28, v29
	v_cvt_pk_bf16_f32 v20, v30, v31
	v_cvt_pk_bf16_f32 v21, v32, v33
	v_cndmask_b32_e64 v40, v42, 0, s[80:81]
	v_cndmask_b32_e64 v41, v43, 0, s[84:85]
	v_cndmask_b32_e64 v42, v44, 0, s[88:89]
	v_cndmask_b32_e64 v43, v45, 0, s[92:93]
	v_cndmask_b32_e64 v44, v46, 0, s[96:97]
	v_cndmask_b32_e64 v45, v47, 0, s[6:7]
	v_cndmask_b32_e64 v46, v48, 0, s[10:11]
	v_cndmask_b32_e64 v47, v49, 0, s[14:15]
	ds_write2_b64 v24, v[18:19], v[20:21] offset0:132 offset1:134
	v_cvt_pk_bf16_f32 v18, v34, v35
	v_cvt_pk_bf16_f32 v19, v36, v37
	v_cvt_pk_bf16_f32 v20, v22, v23
	v_cvt_pk_bf16_f32 v21, v38, v39
	ds_write2_b64 v184, v[18:19], v[20:21] offset0:128 offset1:130
	v_cvt_pk_bf16_f32 v18, v40, v41
	v_cvt_pk_bf16_f32 v19, v42, v43
	v_cvt_pk_bf16_f32 v20, v44, v45
	v_cvt_pk_bf16_f32 v21, v46, v47
	v_mov_b32_e32 v23, v110
	ds_write2_b64 v184, v[18:19], v[20:21] offset0:132 offset1:134
	s_waitcnt lgkmcnt(0)
	s_barrier
	v_mfma_f32_32x32x16_bf16 v[2:17], v[92:95], v[96:99], 0
	v_mfma_f32_32x32x16_bf16 v[2:17], v[100:103], v[196:199], v[2:17]
	v_mfma_f32_32x32x16_bf16 v[2:17], v[186:189], v[204:207], v[2:17]
	v_mfma_f32_32x32x16_bf16 v[2:17], v[200:203], v[212:215], v[2:17]
	v_readfirstlane_b32 s98, v0
	v_and_b32_e32 v243, 15, v0
	s_lshr_b32 s99, s98, 1
	s_xor_b32 s99, s99, s98
	s_bitcmp1_b32 s99, 7
	s_cbranch_scc1 .Ls3_idle
	v_lshl_add_u32 v228, v243, 2, v23
	v_mul_u32_u24_e32 v229, 0x110, v243
	v_add_u32_e32 v229, v229, v23
	v_bfe_u32 v243, v0, 4, 2
	v_lshl_add_u32 v229, v243, 2, v229
	v_and_b32_e32 v243, 63, v0
	s_bfe_u32 s98, s98, 0x10006
	s_mul_i32 s99, s98, 0x2400
	s_add_i32 s99, s99, 0xffffb800
	v_lshl_add_u32 v232, v243, 1, v23
	v_add_u32_e32 v232, s99, v232
	v_lshl_or_b32 v233, s98, 6, v243
	v_mul_u32_u24_e32 v233, 0x90, v233
	s_mov_b32 s99, 0xffff2800
	v_add3_u32 v233, v233, v23, s99
	ds_read_u16 v18, v232
	ds_read_u16 v19, v232 offset:144
	ds_read_u16 v20, v232 offset:288
	ds_read_u16 v21, v232 offset:432
	ds_read_u16 v22, v232 offset:576
	ds_read_u16 v24, v232 offset:720
	ds_read_u16 v25, v232 offset:864
	ds_read_u16 v26, v232 offset:1008
	ds_read_u16 v27, v232 offset:1152
	ds_read_u16 v28, v232 offset:1296
	ds_read_u16 v29, v232 offset:1440
	ds_read_u16 v30, v232 offset:1584
	s_waitcnt lgkmcnt(0)
	ds_read_u16 v31, v232 offset:1728
	ds_read_u16 v32, v232 offset:1872
	ds_read_u16 v33, v232 offset:2016
	ds_read_u16 v34, v232 offset:2160
	v_lshlrev_b32_e32 v18, 16, v18
	v_lshlrev_b32_e32 v19, 16, v19
	v_lshlrev_b32_e32 v20, 16, v20
	v_lshlrev_b32_e32 v21, 16, v21
	v_lshlrev_b32_e32 v22, 16, v22
	v_lshlrev_b32_e32 v24, 16, v24
	v_lshlrev_b32_e32 v25, 16, v25
	v_lshlrev_b32_e32 v26, 16, v26
	v_lshlrev_b32_e32 v27, 16, v27
	v_lshlrev_b32_e32 v28, 16, v28
	v_lshlrev_b32_e32 v29, 16, v29
	v_lshlrev_b32_e32 v30, 16, v30
	s_waitcnt lgkmcnt(0)
	v_lshlrev_b32_e32 v31, 16, v31
	v_lshlrev_b32_e32 v32, 16, v32
	v_lshlrev_b32_e32 v33, 16, v33
	v_lshlrev_b32_e32 v34, 16, v34
	ds_read_b32 v234, v228 offset:272
	ds_read_b32 v235, v228 offset:544
	ds_read_b32 v242, v228 offset:816
	s_waitcnt lgkmcnt(2)
	v_fmac_f32_dpp v19, v234, v18 row_newbcast:0 row_mask:0xf bank_mask:0xf
	ds_read_b32 v234, v228 offset:1088
	s_waitcnt lgkmcnt(2)
	v_fmac_f32_dpp v20, v235, v18 row_newbcast:0 row_mask:0xf bank_mask:0xf
	v_mul_f32_dpp v243, v235, v19 row_newbcast:1 row_mask:0xf bank_mask:0xf
	v_add_f32_e32 v20, v20, v243
	ds_read_b32 v235, v228 offset:1360
	s_waitcnt lgkmcnt(2)
	v_fmac_f32_dpp v21, v242, v18 row_newbcast:0 row_mask:0xf bank_mask:0xf
	v_mul_f32_dpp v243, v242, v19 row_newbcast:1 row_mask:0xf bank_mask:0xf
	v_mul_f32_dpp v244, v242, v20 row_newbcast:2 row_mask:0xf bank_mask:0xf
	v_add_f32_e32 v21, v21, v243
	v_add_f32_e32 v21, v21, v244
	ds_read_b32 v242, v228 offset:1632
	s_waitcnt lgkmcnt(2)
	v_fmac_f32_dpp v22, v234, v18 row_newbcast:0 row_mask:0xf bank_mask:0xf
	v_mul_f32_dpp v243, v234, v19 row_newbcast:1 row_mask:0xf bank_mask:0xf
	v_mul_f32_dpp v244, v234, v20 row_newbcast:2 row_mask:0xf bank_mask:0xf
	v_mul_f32_dpp v245, v234, v21 row_newbcast:3 row_mask:0xf bank_mask:0xf
	v_add_f32_e32 v22, v22, v243
	v_add_f32_e32 v244, v244, v245
	v_add_f32_e32 v22, v22, v244
	ds_read_b32 v234, v228 offset:1904
	s_waitcnt lgkmcnt(2)
	v_fmac_f32_dpp v24, v235, v18 row_newbcast:0 row_mask:0xf bank_mask:0xf
	v_mul_f32_dpp v243, v235, v19 row_newbcast:1 row_mask:0xf bank_mask:0xf
	v_mul_f32_dpp v244, v235, v20 row_newbcast:2 row_mask:0xf bank_mask:0xf
	v_mul_f32_dpp v245, v235, v21 row_newbcast:3 row_mask:0xf bank_mask:0xf
	v_fmac_f32_dpp v24, v235, v22 row_newbcast:4 row_mask:0xf bank_mask:0xf
	v_add_f32_e32 v24, v24, v243
	v_add_f32_e32 v244, v244, v245
	v_add_f32_e32 v24, v24, v244
	ds_read_b32 v235, v228 offset:2176
	s_waitcnt lgkmcnt(2)
	v_fmac_f32_dpp v25, v242, v18 row_newbcast:0 row_mask:0xf bank_mask:0xf
	v_mul_f32_dpp v243, v242, v19 row_newbcast:1 row_mask:0xf bank_mask:0xf
	v_mul_f32_dpp v244, v242, v20 row_newbcast:2 row_mask:0xf bank_mask:0xf
	v_mul_f32_dpp v245, v242, v21 row_newbcast:3 row_mask:0xf bank_mask:0xf
	v_fmac_f32_dpp v25, v242, v22 row_newbcast:4 row_mask:0xf bank_mask:0xf
	v_fmac_f32_dpp v243, v242, v24 row_newbcast:5 row_mask:0xf bank_mask:0xf
	v_add_f32_e32 v25, v25, v243
	v_add_f32_e32 v244, v244, v245
	v_add_f32_e32 v25, v25, v244
	ds_read_b32 v242, v228 offset:2448
	s_waitcnt lgkmcnt(2)
	v_fmac_f32_dpp v26, v234, v18 row_newbcast:0 row_mask:0xf bank_mask:0xf
	v_mul_f32_dpp v243, v234, v19 row_newbcast:1 row_mask:0xf bank_mask:0xf
	v_mul_f32_dpp v244, v234, v20 row_newbcast:2 row_mask:0xf bank_mask:0xf
	v_mul_f32_dpp v245, v234, v21 row_newbcast:3 row_mask:0xf bank_mask:0xf
	v_fmac_f32_dpp v26, v234, v22 row_newbcast:4 row_mask:0xf bank_mask:0xf
	v_fmac_f32_dpp v243, v234, v24 row_newbcast:5 row_mask:0xf bank_mask:0xf
	v_fmac_f32_dpp v244, v234, v25 row_newbcast:6 row_mask:0xf bank_mask:0xf
	v_add_f32_e32 v26, v26, v243
	v_add_f32_e32 v244, v244, v245
	v_add_f32_e32 v26, v26, v244
	ds_read_b32 v234, v228 offset:2720
	s_waitcnt lgkmcnt(2)
	v_fmac_f32_dpp v27, v235, v18 row_newbcast:0 row_mask:0xf bank_mask:0xf
	v_mul_f32_dpp v243, v235, v19 row_newbcast:1 row_mask:0xf bank_mask:0xf
	v_mul_f32_dpp v244, v235, v20 row_newbcast:2 row_mask:0xf bank_mask:0xf
	v_mul_f32_dpp v245, v235, v21 row_newbcast:3 row_mask:0xf bank_mask:0xf
	v_fmac_f32_dpp v27, v235, v22 row_newbcast:4 row_mask:0xf bank_mask:0xf
	v_fmac_f32_dpp v243, v235, v24 row_newbcast:5 row_mask:0xf bank_mask:0xf
	v_fmac_f32_dpp v244, v235, v25 row_newbcast:6 row_mask:0xf bank_mask:0xf
	v_fmac_f32_dpp v245, v235, v26 row_newbcast:7 row_mask:0xf bank_mask:0xf
	v_add_f32_e32 v27, v27, v243
	v_add_f32_e32 v244, v244, v245
	v_add_f32_e32 v27, v27, v244
	ds_read_b32 v235, v228 offset:2992
	s_waitcnt lgkmcnt(2)
	v_fmac_f32_dpp v28, v242, v18 row_newbcast:0 row_mask:0xf bank_mask:0xf
	v_mul_f32_dpp v243, v242, v19 row_newbcast:1 row_mask:0xf bank_mask:0xf
	v_mul_f32_dpp v244, v242, v20 row_newbcast:2 row_mask:0xf bank_mask:0xf
	v_mul_f32_dpp v245, v242, v21 row_newbcast:3 row_mask:0xf bank_mask:0xf
	v_fmac_f32_dpp v28, v242, v22 row_newbcast:4 row_mask:0xf bank_mask:0xf
	v_fmac_f32_dpp v243, v242, v24 row_newbcast:5 row_mask:0xf bank_mask:0xf
	v_fmac_f32_dpp v244, v242, v25 row_newbcast:6 row_mask:0xf bank_mask:0xf
	v_fmac_f32_dpp v245, v242, v26 row_newbcast:7 row_mask:0xf bank_mask:0xf
	v_fmac_f32_dpp v28, v242, v27 row_newbcast:8 row_mask:0xf bank_mask:0xf
	v_add_f32_e32 v28, v28, v243
	v_add_f32_e32 v244, v244, v245
	v_add_f32_e32 v28, v28, v244
	ds_read_b32 v242, v228 offset:3264
	s_waitcnt lgkmcnt(2)
	v_fmac_f32_dpp v29, v234, v18 row_newbcast:0 row_mask:0xf bank_mask:0xf
	v_mul_f32_dpp v243, v234, v19 row_newbcast:1 row_mask:0xf bank_mask:0xf
	v_mul_f32_dpp v244, v234, v20 row_newbcast:2 row_mask:0xf bank_mask:0xf
	v_mul_f32_dpp v245, v234, v21 row_newbcast:3 row_mask:0xf bank_mask:0xf
	v_fmac_f32_dpp v29, v234, v22 row_newbcast:4 row_mask:0xf bank_mask:0xf
	v_fmac_f32_dpp v243, v234, v24 row_newbcast:5 row_mask:0xf bank_mask:0xf
	v_fmac_f32_dpp v244, v234, v25 row_newbcast:6 row_mask:0xf bank_mask:0xf
	v_fmac_f32_dpp v245, v234, v26 row_newbcast:7 row_mask:0xf bank_mask:0xf
	v_fmac_f32_dpp v29, v234, v27 row_newbcast:8 row_mask:0xf bank_mask:0xf
	v_fmac_f32_dpp v243, v234, v28 row_newbcast:9 row_mask:0xf bank_mask:0xf
	v_add_f32_e32 v29, v29, v243
	v_add_f32_e32 v244, v244, v245
	v_add_f32_e32 v29, v29, v244
	ds_read_b32 v234, v228 offset:3536
	s_waitcnt lgkmcnt(2)
	v_fmac_f32_dpp v30, v235, v18 row_newbcast:0 row_mask:0xf bank_mask:0xf
	v_mul_f32_dpp v243, v235, v19 row_newbcast:1 row_mask:0xf bank_mask:0xf
	v_mul_f32_dpp v244, v235, v20 row_newbcast:2 row_mask:0xf bank_mask:0xf
	v_mul_f32_dpp v245, v235, v21 row_newbcast:3 row_mask:0xf bank_mask:0xf
	v_fmac_f32_dpp v30, v235, v22 row_newbcast:4 row_mask:0xf bank_mask:0xf
	v_fmac_f32_dpp v243, v235, v24 row_newbcast:5 row_mask:0xf bank_mask:0xf
	v_fmac_f32_dpp v244, v235, v25 row_newbcast:6 row_mask:0xf bank_mask:0xf
	v_fmac_f32_dpp v245, v235, v26 row_newbcast:7 row_mask:0xf bank_mask:0xf
	v_fmac_f32_dpp v30, v235, v27 row_newbcast:8 row_mask:0xf bank_mask:0xf
	v_fmac_f32_dpp v243, v235, v28 row_newbcast:9 row_mask:0xf bank_mask:0xf
	v_fmac_f32_dpp v244, v235, v29 row_newbcast:10 row_mask:0xf bank_mask:0xf
	v_add_f32_e32 v30, v30, v243
	v_add_f32_e32 v244, v244, v245
	v_add_f32_e32 v30, v30, v244
	ds_read_b32 v235, v228 offset:3808
	s_waitcnt lgkmcnt(2)
	v_fmac_f32_dpp v31, v242, v18 row_newbcast:0 row_mask:0xf bank_mask:0xf
	v_mul_f32_dpp v243, v242, v19 row_newbcast:1 row_mask:0xf bank_mask:0xf
	v_mul_f32_dpp v244, v242, v20 row_newbcast:2 row_mask:0xf bank_mask:0xf
	v_mul_f32_dpp v245, v242, v21 row_newbcast:3 row_mask:0xf bank_mask:0xf
	v_fmac_f32_dpp v31, v242, v22 row_newbcast:4 row_mask:0xf bank_mask:0xf
	v_fmac_f32_dpp v243, v242, v24 row_newbcast:5 row_mask:0xf bank_mask:0xf
	v_fmac_f32_dpp v244, v242, v25 row_newbcast:6 row_mask:0xf bank_mask:0xf
	v_fmac_f32_dpp v245, v242, v26 row_newbcast:7 row_mask:0xf bank_mask:0xf
	v_fmac_f32_dpp v31, v242, v27 row_newbcast:8 row_mask:0xf bank_mask:0xf
	v_fmac_f32_dpp v243, v242, v28 row_newbcast:9 row_mask:0xf bank_mask:0xf
	v_fmac_f32_dpp v244, v242, v29 row_newbcast:10 row_mask:0xf bank_mask:0xf
	v_fmac_f32_dpp v245, v242, v30 row_newbcast:11 row_mask:0xf bank_mask:0xf
	v_add_f32_e32 v31, v31, v243
	v_add_f32_e32 v244, v244, v245
	v_add_f32_e32 v31, v31, v244
	ds_read_b32 v242, v228 offset:4080
	s_waitcnt lgkmcnt(2)
	v_fmac_f32_dpp v32, v234, v18 row_newbcast:0 row_mask:0xf bank_mask:0xf
	v_mul_f32_dpp v243, v234, v19 row_newbcast:1 row_mask:0xf bank_mask:0xf
	v_mul_f32_dpp v244, v234, v20 row_newbcast:2 row_mask:0xf bank_mask:0xf
	v_mul_f32_dpp v245, v234, v21 row_newbcast:3 row_mask:0xf bank_mask:0xf
	v_fmac_f32_dpp v32, v234, v22 row_newbcast:4 row_mask:0xf bank_mask:0xf
	v_fmac_f32_dpp v243, v234, v24 row_newbcast:5 row_mask:0xf bank_mask:0xf
	v_fmac_f32_dpp v244, v234, v25 row_newbcast:6 row_mask:0xf bank_mask:0xf
	v_fmac_f32_dpp v245, v234, v26 row_newbcast:7 row_mask:0xf bank_mask:0xf
	v_fmac_f32_dpp v32, v234, v27 row_newbcast:8 row_mask:0xf bank_mask:0xf
	v_fmac_f32_dpp v243, v234, v28 row_newbcast:9 row_mask:0xf bank_mask:0xf
	v_fmac_f32_dpp v244, v234, v29 row_newbcast:10 row_mask:0xf bank_mask:0xf
	v_fmac_f32_dpp v245, v234, v30 row_newbcast:11 row_mask:0xf bank_mask:0xf
	v_fmac_f32_dpp v32, v234, v31 row_newbcast:12 row_mask:0xf bank_mask:0xf
	v_add_f32_e32 v32, v32, v243
	v_add_f32_e32 v244, v244, v245
	v_add_f32_e32 v32, v32, v244
	s_waitcnt lgkmcnt(1)
	v_fmac_f32_dpp v33, v235, v18 row_newbcast:0 row_mask:0xf bank_mask:0xf
	v_mul_f32_dpp v243, v235, v19 row_newbcast:1 row_mask:0xf bank_mask:0xf
	v_mul_f32_dpp v244, v235, v20 row_newbcast:2 row_mask:0xf bank_mask:0xf
	v_mul_f32_dpp v245, v235, v21 row_newbcast:3 row_mask:0xf bank_mask:0xf
	v_fmac_f32_dpp v33, v235, v22 row_newbcast:4 row_mask:0xf bank_mask:0xf
	v_fmac_f32_dpp v243, v235, v24 row_newbcast:5 row_mask:0xf bank_mask:0xf
	v_fmac_f32_dpp v244, v235, v25 row_newbcast:6 row_mask:0xf bank_mask:0xf
	v_fmac_f32_dpp v245, v235, v26 row_newbcast:7 row_mask:0xf bank_mask:0xf
	v_fmac_f32_dpp v33, v235, v27 row_newbcast:8 row_mask:0xf bank_mask:0xf
	v_fmac_f32_dpp v243, v235, v28 row_newbcast:9 row_mask:0xf bank_mask:0xf
	v_fmac_f32_dpp v244, v235, v29 row_newbcast:10 row_mask:0xf bank_mask:0xf
	v_fmac_f32_dpp v245, v235, v30 row_newbcast:11 row_mask:0xf bank_mask:0xf
	v_fmac_f32_dpp v33, v235, v31 row_newbcast:12 row_mask:0xf bank_mask:0xf
	v_fmac_f32_dpp v243, v235, v32 row_newbcast:13 row_mask:0xf bank_mask:0xf
	v_add_f32_e32 v33, v33, v243
	v_add_f32_e32 v244, v244, v245
	v_add_f32_e32 v33, v33, v244
	s_waitcnt lgkmcnt(0)
	v_fmac_f32_dpp v34, v242, v18 row_newbcast:0 row_mask:0xf bank_mask:0xf
	v_mul_f32_dpp v243, v242, v19 row_newbcast:1 row_mask:0xf bank_mask:0xf
	v_mul_f32_dpp v244, v242, v20 row_newbcast:2 row_mask:0xf bank_mask:0xf
	v_mul_f32_dpp v245, v242, v21 row_newbcast:3 row_mask:0xf bank_mask:0xf
	v_fmac_f32_dpp v34, v242, v22 row_newbcast:4 row_mask:0xf bank_mask:0xf
	v_fmac_f32_dpp v243, v242, v24 row_newbcast:5 row_mask:0xf bank_mask:0xf
	v_fmac_f32_dpp v244, v242, v25 row_newbcast:6 row_mask:0xf bank_mask:0xf
	v_fmac_f32_dpp v245, v242, v26 row_newbcast:7 row_mask:0xf bank_mask:0xf
	v_fmac_f32_dpp v34, v242, v27 row_newbcast:8 row_mask:0xf bank_mask:0xf
	v_fmac_f32_dpp v243, v242, v28 row_newbcast:9 row_mask:0xf bank_mask:0xf
	v_fmac_f32_dpp v244, v242, v29 row_newbcast:10 row_mask:0xf bank_mask:0xf
	v_fmac_f32_dpp v245, v242, v30 row_newbcast:11 row_mask:0xf bank_mask:0xf
	v_fmac_f32_dpp v34, v242, v31 row_newbcast:12 row_mask:0xf bank_mask:0xf
	v_fmac_f32_dpp v243, v242, v32 row_newbcast:13 row_mask:0xf bank_mask:0xf
	v_fmac_f32_dpp v244, v242, v33 row_newbcast:14 row_mask:0xf bank_mask:0xf
	v_add_f32_e32 v34, v34, v243
	v_add_f32_e32 v244, v244, v245
	v_add_f32_e32 v34, v34, v244
	s_nop 1
	v_permlane32_swap_b32_e32 v18, v20
	v_permlane32_swap_b32_e32 v19, v21
	v_permlane32_swap_b32_e32 v22, v25
	v_permlane32_swap_b32_e32 v24, v26
	v_permlane32_swap_b32_e32 v27, v29
	v_permlane32_swap_b32_e32 v28, v30
	v_permlane32_swap_b32_e32 v31, v33
	v_permlane32_swap_b32_e32 v32, v34
	v_permlane16_swap_b32_e32 v18, v19
	v_permlane16_swap_b32_e32 v20, v21
	v_permlane16_swap_b32_e32 v22, v24
	v_permlane16_swap_b32_e32 v25, v26
	v_permlane16_swap_b32_e32 v27, v28
	v_permlane16_swap_b32_e32 v29, v30
	v_permlane16_swap_b32_e32 v31, v32
	v_permlane16_swap_b32_e32 v33, v34
	s_nop 1
	ds_read_u16 v35, v232 offset:2304
	ds_read_u16 v36, v232 offset:2448
	ds_read_u16 v37, v232 offset:2592
	ds_read_u16 v38, v232 offset:2736
	ds_read_u16 v39, v232 offset:2880
	ds_read_u16 v40, v232 offset:3024
	ds_read_u16 v41, v232 offset:3168
	ds_read_u16 v42, v232 offset:3312
	ds_read_b32 v234, v229 offset:4352
	ds_read_b32 v235, v229 offset:4368
	ds_read_b32 v242, v229 offset:4384
	ds_read_b32 v243, v229 offset:4400
	s_waitcnt lgkmcnt(3)
	v_mfma_f32_16x16x4_f32 v[204:207], v234, v18, 0
	v_mfma_f32_16x16x4_f32 v[208:211], v234, v19, 0
	v_mfma_f32_16x16x4_f32 v[212:215], v234, v20, 0
	v_mfma_f32_16x16x4_f32 v[222:225], v234, v21, 0
	s_waitcnt lgkmcnt(2)
	v_mfma_f32_16x16x4_f32 v[204:207], v235, v22, v[204:207]
	v_mfma_f32_16x16x4_f32 v[208:211], v235, v24, v[208:211]
	v_mfma_f32_16x16x4_f32 v[212:215], v235, v25, v[212:215]
	v_mfma_f32_16x16x4_f32 v[222:225], v235, v26, v[222:225]
	s_waitcnt lgkmcnt(1)
	v_mfma_f32_16x16x4_f32 v[204:207], v242, v27, v[204:207]
	v_mfma_f32_16x16x4_f32 v[208:211], v242, v28, v[208:211]
	v_mfma_f32_16x16x4_f32 v[212:215], v242, v29, v[212:215]
	v_mfma_f32_16x16x4_f32 v[222:225], v242, v30, v[222:225]
	s_waitcnt lgkmcnt(0)
	v_mfma_f32_16x16x4_f32 v[204:207], v243, v31, v[204:207]
	v_mfma_f32_16x16x4_f32 v[208:211], v243, v32, v[208:211]
	v_mfma_f32_16x16x4_f32 v[212:215], v243, v33, v[212:215]
	v_mfma_f32_16x16x4_f32 v[222:225], v243, v34, v[222:225]
	ds_read_u16 v43, v232 offset:3456
	ds_read_u16 v44, v232 offset:3600
	ds_read_u16 v45, v232 offset:3744
	ds_read_u16 v46, v232 offset:3888
	ds_read_u16 v47, v232 offset:4032
	ds_read_u16 v48, v232 offset:4176
	ds_read_u16 v49, v232 offset:4320
	ds_read_u16 v91, v232 offset:4464
	s_waitcnt lgkmcnt(0)
	v_lshlrev_b32_e32 v35, 16, v35
	v_lshlrev_b32_e32 v36, 16, v36
	v_lshlrev_b32_e32 v37, 16, v37
	v_lshlrev_b32_e32 v38, 16, v38
	v_lshlrev_b32_e32 v39, 16, v39
	v_lshlrev_b32_e32 v40, 16, v40
	v_lshlrev_b32_e32 v41, 16, v41
	v_lshlrev_b32_e32 v42, 16, v42
	v_lshlrev_b32_e32 v43, 16, v43
	v_lshlrev_b32_e32 v44, 16, v44
	v_lshlrev_b32_e32 v45, 16, v45
	v_lshlrev_b32_e32 v46, 16, v46
	v_lshlrev_b32_e32 v47, 16, v47
	v_lshlrev_b32_e32 v48, 16, v48
	v_lshlrev_b32_e32 v49, 16, v49
	v_lshlrev_b32_e32 v91, 16, v91
	s_nop 10
	s_nop 1
	v_permlane32_swap_b32_e32 v204, v212
	v_permlane32_swap_b32_e32 v208, v222
	v_permlane32_swap_b32_e32 v205, v213
	v_permlane32_swap_b32_e32 v209, v223
	v_permlane32_swap_b32_e32 v206, v214
	v_permlane32_swap_b32_e32 v210, v224
	v_permlane32_swap_b32_e32 v207, v215
	v_permlane32_swap_b32_e32 v211, v225
	v_permlane16_swap_b32_e32 v204, v208
	v_permlane16_swap_b32_e32 v212, v222
	v_permlane16_swap_b32_e32 v205, v209
	v_permlane16_swap_b32_e32 v213, v223
	v_permlane16_swap_b32_e32 v206, v210
	v_permlane16_swap_b32_e32 v214, v224
	v_permlane16_swap_b32_e32 v207, v211
	v_permlane16_swap_b32_e32 v215, v225
	s_nop 1
	v_add_f32_e32 v35, v35, v204
	v_add_f32_e32 v39, v39, v208
	v_add_f32_e32 v43, v43, v212
	v_add_f32_e32 v47, v47, v222
	v_add_f32_e32 v36, v36, v205
	v_add_f32_e32 v40, v40, v209
	v_add_f32_e32 v44, v44, v213
	v_add_f32_e32 v48, v48, v223
	v_add_f32_e32 v37, v37, v206
	v_add_f32_e32 v41, v41, v210
	v_add_f32_e32 v45, v45, v214
	v_add_f32_e32 v49, v49, v224
	v_add_f32_e32 v38, v38, v207
	v_add_f32_e32 v42, v42, v211
	v_add_f32_e32 v46, v46, v215
	v_add_f32_e32 v91, v91, v225
	ds_read_b32 v234, v228 offset:4688
	ds_read_b32 v235, v228 offset:4960
	ds_read_b32 v242, v228 offset:5232
	s_waitcnt lgkmcnt(2)
	v_fmac_f32_dpp v36, v234, v35 row_newbcast:0 row_mask:0xf bank_mask:0xf
	ds_read_b32 v234, v228 offset:5504
	s_waitcnt lgkmcnt(2)
	v_fmac_f32_dpp v37, v235, v35 row_newbcast:0 row_mask:0xf bank_mask:0xf
	v_mul_f32_dpp v243, v235, v36 row_newbcast:1 row_mask:0xf bank_mask:0xf
	v_add_f32_e32 v37, v37, v243
	ds_read_b32 v235, v228 offset:5776
	s_waitcnt lgkmcnt(2)
	v_fmac_f32_dpp v38, v242, v35 row_newbcast:0 row_mask:0xf bank_mask:0xf
	v_mul_f32_dpp v243, v242, v36 row_newbcast:1 row_mask:0xf bank_mask:0xf
	v_mul_f32_dpp v244, v242, v37 row_newbcast:2 row_mask:0xf bank_mask:0xf
	v_add_f32_e32 v38, v38, v243
	v_add_f32_e32 v38, v38, v244
	ds_read_b32 v242, v228 offset:6048
	s_waitcnt lgkmcnt(2)
	v_fmac_f32_dpp v39, v234, v35 row_newbcast:0 row_mask:0xf bank_mask:0xf
	v_mul_f32_dpp v243, v234, v36 row_newbcast:1 row_mask:0xf bank_mask:0xf
	v_mul_f32_dpp v244, v234, v37 row_newbcast:2 row_mask:0xf bank_mask:0xf
	v_mul_f32_dpp v245, v234, v38 row_newbcast:3 row_mask:0xf bank_mask:0xf
	v_add_f32_e32 v39, v39, v243
	v_add_f32_e32 v244, v244, v245
	v_add_f32_e32 v39, v39, v244
	ds_read_b32 v234, v228 offset:6320
	s_waitcnt lgkmcnt(2)
	v_fmac_f32_dpp v40, v235, v35 row_newbcast:0 row_mask:0xf bank_mask:0xf
	v_mul_f32_dpp v243, v235, v36 row_newbcast:1 row_mask:0xf bank_mask:0xf
	v_mul_f32_dpp v244, v235, v37 row_newbcast:2 row_mask:0xf bank_mask:0xf
	v_mul_f32_dpp v245, v235, v38 row_newbcast:3 row_mask:0xf bank_mask:0xf
	v_fmac_f32_dpp v40, v235, v39 row_newbcast:4 row_mask:0xf bank_mask:0xf
	v_add_f32_e32 v40, v40, v243
	v_add_f32_e32 v244, v244, v245
	v_add_f32_e32 v40, v40, v244
	ds_read_b32 v235, v228 offset:6592
	s_waitcnt lgkmcnt(2)
	v_fmac_f32_dpp v41, v242, v35 row_newbcast:0 row_mask:0xf bank_mask:0xf
	v_mul_f32_dpp v243, v242, v36 row_newbcast:1 row_mask:0xf bank_mask:0xf
	v_mul_f32_dpp v244, v242, v37 row_newbcast:2 row_mask:0xf bank_mask:0xf
	v_mul_f32_dpp v245, v242, v38 row_newbcast:3 row_mask:0xf bank_mask:0xf
	v_fmac_f32_dpp v41, v242, v39 row_newbcast:4 row_mask:0xf bank_mask:0xf
	v_fmac_f32_dpp v243, v242, v40 row_newbcast:5 row_mask:0xf bank_mask:0xf
	v_add_f32_e32 v41, v41, v243
	v_add_f32_e32 v244, v244, v245
	v_add_f32_e32 v41, v41, v244
	ds_read_b32 v242, v228 offset:6864
	s_waitcnt lgkmcnt(2)
	v_fmac_f32_dpp v42, v234, v35 row_newbcast:0 row_mask:0xf bank_mask:0xf
	v_mul_f32_dpp v243, v234, v36 row_newbcast:1 row_mask:0xf bank_mask:0xf
	v_mul_f32_dpp v244, v234, v37 row_newbcast:2 row_mask:0xf bank_mask:0xf
	v_mul_f32_dpp v245, v234, v38 row_newbcast:3 row_mask:0xf bank_mask:0xf
	v_fmac_f32_dpp v42, v234, v39 row_newbcast:4 row_mask:0xf bank_mask:0xf
	v_fmac_f32_dpp v243, v234, v40 row_newbcast:5 row_mask:0xf bank_mask:0xf
	v_fmac_f32_dpp v244, v234, v41 row_newbcast:6 row_mask:0xf bank_mask:0xf
	v_add_f32_e32 v42, v42, v243
	v_add_f32_e32 v244, v244, v245
	v_add_f32_e32 v42, v42, v244
	ds_read_b32 v234, v228 offset:7136
	s_waitcnt lgkmcnt(2)
	v_fmac_f32_dpp v43, v235, v35 row_newbcast:0 row_mask:0xf bank_mask:0xf
	v_mul_f32_dpp v243, v235, v36 row_newbcast:1 row_mask:0xf bank_mask:0xf
	v_mul_f32_dpp v244, v235, v37 row_newbcast:2 row_mask:0xf bank_mask:0xf
	v_mul_f32_dpp v245, v235, v38 row_newbcast:3 row_mask:0xf bank_mask:0xf
	v_fmac_f32_dpp v43, v235, v39 row_newbcast:4 row_mask:0xf bank_mask:0xf
	v_fmac_f32_dpp v243, v235, v40 row_newbcast:5 row_mask:0xf bank_mask:0xf
	v_fmac_f32_dpp v244, v235, v41 row_newbcast:6 row_mask:0xf bank_mask:0xf
	v_fmac_f32_dpp v245, v235, v42 row_newbcast:7 row_mask:0xf bank_mask:0xf
	v_add_f32_e32 v43, v43, v243
	v_add_f32_e32 v244, v244, v245
	v_add_f32_e32 v43, v43, v244
	ds_read_b32 v235, v228 offset:7408
	s_waitcnt lgkmcnt(2)
	v_fmac_f32_dpp v44, v242, v35 row_newbcast:0 row_mask:0xf bank_mask:0xf
	v_mul_f32_dpp v243, v242, v36 row_newbcast:1 row_mask:0xf bank_mask:0xf
	v_mul_f32_dpp v244, v242, v37 row_newbcast:2 row_mask:0xf bank_mask:0xf
	v_mul_f32_dpp v245, v242, v38 row_newbcast:3 row_mask:0xf bank_mask:0xf
	v_fmac_f32_dpp v44, v242, v39 row_newbcast:4 row_mask:0xf bank_mask:0xf
	v_fmac_f32_dpp v243, v242, v40 row_newbcast:5 row_mask:0xf bank_mask:0xf
	v_fmac_f32_dpp v244, v242, v41 row_newbcast:6 row_mask:0xf bank_mask:0xf
	v_fmac_f32_dpp v245, v242, v42 row_newbcast:7 row_mask:0xf bank_mask:0xf
	v_fmac_f32_dpp v44, v242, v43 row_newbcast:8 row_mask:0xf bank_mask:0xf
	v_add_f32_e32 v44, v44, v243
	v_add_f32_e32 v244, v244, v245
	v_add_f32_e32 v44, v44, v244
	ds_read_b32 v242, v228 offset:7680
	s_waitcnt lgkmcnt(2)
	v_fmac_f32_dpp v45, v234, v35 row_newbcast:0 row_mask:0xf bank_mask:0xf
	v_mul_f32_dpp v243, v234, v36 row_newbcast:1 row_mask:0xf bank_mask:0xf
	v_mul_f32_dpp v244, v234, v37 row_newbcast:2 row_mask:0xf bank_mask:0xf
	v_mul_f32_dpp v245, v234, v38 row_newbcast:3 row_mask:0xf bank_mask:0xf
	v_fmac_f32_dpp v45, v234, v39 row_newbcast:4 row_mask:0xf bank_mask:0xf
	v_fmac_f32_dpp v243, v234, v40 row_newbcast:5 row_mask:0xf bank_mask:0xf
	v_fmac_f32_dpp v244, v234, v41 row_newbcast:6 row_mask:0xf bank_mask:0xf
	v_fmac_f32_dpp v245, v234, v42 row_newbcast:7 row_mask:0xf bank_mask:0xf
	v_fmac_f32_dpp v45, v234, v43 row_newbcast:8 row_mask:0xf bank_mask:0xf
	v_fmac_f32_dpp v243, v234, v44 row_newbcast:9 row_mask:0xf bank_mask:0xf
	v_add_f32_e32 v45, v45, v243
	v_add_f32_e32 v244, v244, v245
	v_add_f32_e32 v45, v45, v244
	ds_read_b32 v234, v228 offset:7952
	s_waitcnt lgkmcnt(2)
	v_fmac_f32_dpp v46, v235, v35 row_newbcast:0 row_mask:0xf bank_mask:0xf
	v_mul_f32_dpp v243, v235, v36 row_newbcast:1 row_mask:0xf bank_mask:0xf
	v_mul_f32_dpp v244, v235, v37 row_newbcast:2 row_mask:0xf bank_mask:0xf
	v_mul_f32_dpp v245, v235, v38 row_newbcast:3 row_mask:0xf bank_mask:0xf
	v_fmac_f32_dpp v46, v235, v39 row_newbcast:4 row_mask:0xf bank_mask:0xf
	v_fmac_f32_dpp v243, v235, v40 row_newbcast:5 row_mask:0xf bank_mask:0xf
	v_fmac_f32_dpp v244, v235, v41 row_newbcast:6 row_mask:0xf bank_mask:0xf
	v_fmac_f32_dpp v245, v235, v42 row_newbcast:7 row_mask:0xf bank_mask:0xf
	v_fmac_f32_dpp v46, v235, v43 row_newbcast:8 row_mask:0xf bank_mask:0xf
	v_fmac_f32_dpp v243, v235, v44 row_newbcast:9 row_mask:0xf bank_mask:0xf
	v_fmac_f32_dpp v244, v235, v45 row_newbcast:10 row_mask:0xf bank_mask:0xf
	v_add_f32_e32 v46, v46, v243
	v_add_f32_e32 v244, v244, v245
	v_add_f32_e32 v46, v46, v244
	ds_read_b32 v235, v228 offset:8224
	s_waitcnt lgkmcnt(2)
	v_fmac_f32_dpp v47, v242, v35 row_newbcast:0 row_mask:0xf bank_mask:0xf
	v_mul_f32_dpp v243, v242, v36 row_newbcast:1 row_mask:0xf bank_mask:0xf
	v_mul_f32_dpp v244, v242, v37 row_newbcast:2 row_mask:0xf bank_mask:0xf
	v_mul_f32_dpp v245, v242, v38 row_newbcast:3 row_mask:0xf bank_mask:0xf
	v_fmac_f32_dpp v47, v242, v39 row_newbcast:4 row_mask:0xf bank_mask:0xf
	v_fmac_f32_dpp v243, v242, v40 row_newbcast:5 row_mask:0xf bank_mask:0xf
	v_fmac_f32_dpp v244, v242, v41 row_newbcast:6 row_mask:0xf bank_mask:0xf
	v_fmac_f32_dpp v245, v242, v42 row_newbcast:7 row_mask:0xf bank_mask:0xf
	v_fmac_f32_dpp v47, v242, v43 row_newbcast:8 row_mask:0xf bank_mask:0xf
	v_fmac_f32_dpp v243, v242, v44 row_newbcast:9 row_mask:0xf bank_mask:0xf
	v_fmac_f32_dpp v244, v242, v45 row_newbcast:10 row_mask:0xf bank_mask:0xf
	v_fmac_f32_dpp v245, v242, v46 row_newbcast:11 row_mask:0xf bank_mask:0xf
	v_add_f32_e32 v47, v47, v243
	v_add_f32_e32 v244, v244, v245
	v_add_f32_e32 v47, v47, v244
	ds_read_b32 v242, v228 offset:8496
	s_waitcnt lgkmcnt(2)
	v_fmac_f32_dpp v48, v234, v35 row_newbcast:0 row_mask:0xf bank_mask:0xf
	v_mul_f32_dpp v243, v234, v36 row_newbcast:1 row_mask:0xf bank_mask:0xf
	v_mul_f32_dpp v244, v234, v37 row_newbcast:2 row_mask:0xf bank_mask:0xf
	v_mul_f32_dpp v245, v234, v38 row_newbcast:3 row_mask:0xf bank_mask:0xf
	v_fmac_f32_dpp v48, v234, v39 row_newbcast:4 row_mask:0xf bank_mask:0xf
	v_fmac_f32_dpp v243, v234, v40 row_newbcast:5 row_mask:0xf bank_mask:0xf
	v_fmac_f32_dpp v244, v234, v41 row_newbcast:6 row_mask:0xf bank_mask:0xf
	v_fmac_f32_dpp v245, v234, v42 row_newbcast:7 row_mask:0xf bank_mask:0xf
	v_fmac_f32_dpp v48, v234, v43 row_newbcast:8 row_mask:0xf bank_mask:0xf
	v_fmac_f32_dpp v243, v234, v44 row_newbcast:9 row_mask:0xf bank_mask:0xf
	v_fmac_f32_dpp v244, v234, v45 row_newbcast:10 row_mask:0xf bank_mask:0xf
	v_fmac_f32_dpp v245, v234, v46 row_newbcast:11 row_mask:0xf bank_mask:0xf
	v_fmac_f32_dpp v48, v234, v47 row_newbcast:12 row_mask:0xf bank_mask:0xf
	v_add_f32_e32 v48, v48, v243
	v_add_f32_e32 v244, v244, v245
	v_add_f32_e32 v48, v48, v244
	s_waitcnt lgkmcnt(1)
	v_fmac_f32_dpp v49, v235, v35 row_newbcast:0 row_mask:0xf bank_mask:0xf
	v_mul_f32_dpp v243, v235, v36 row_newbcast:1 row_mask:0xf bank_mask:0xf
	v_mul_f32_dpp v244, v235, v37 row_newbcast:2 row_mask:0xf bank_mask:0xf
	v_mul_f32_dpp v245, v235, v38 row_newbcast:3 row_mask:0xf bank_mask:0xf
	v_fmac_f32_dpp v49, v235, v39 row_newbcast:4 row_mask:0xf bank_mask:0xf
	v_fmac_f32_dpp v243, v235, v40 row_newbcast:5 row_mask:0xf bank_mask:0xf
	v_fmac_f32_dpp v244, v235, v41 row_newbcast:6 row_mask:0xf bank_mask:0xf
	v_fmac_f32_dpp v245, v235, v42 row_newbcast:7 row_mask:0xf bank_mask:0xf
	v_fmac_f32_dpp v49, v235, v43 row_newbcast:8 row_mask:0xf bank_mask:0xf
	v_fmac_f32_dpp v243, v235, v44 row_newbcast:9 row_mask:0xf bank_mask:0xf
	v_fmac_f32_dpp v244, v235, v45 row_newbcast:10 row_mask:0xf bank_mask:0xf
	v_fmac_f32_dpp v245, v235, v46 row_newbcast:11 row_mask:0xf bank_mask:0xf
	v_fmac_f32_dpp v49, v235, v47 row_newbcast:12 row_mask:0xf bank_mask:0xf
	v_fmac_f32_dpp v243, v235, v48 row_newbcast:13 row_mask:0xf bank_mask:0xf
	v_add_f32_e32 v49, v49, v243
	v_add_f32_e32 v244, v244, v245
	v_add_f32_e32 v49, v49, v244
	s_waitcnt lgkmcnt(0)
	v_fmac_f32_dpp v91, v242, v35 row_newbcast:0 row_mask:0xf bank_mask:0xf
	v_mul_f32_dpp v243, v242, v36 row_newbcast:1 row_mask:0xf bank_mask:0xf
	v_mul_f32_dpp v244, v242, v37 row_newbcast:2 row_mask:0xf bank_mask:0xf
	v_mul_f32_dpp v245, v242, v38 row_newbcast:3 row_mask:0xf bank_mask:0xf
	v_fmac_f32_dpp v91, v242, v39 row_newbcast:4 row_mask:0xf bank_mask:0xf
	v_fmac_f32_dpp v243, v242, v40 row_newbcast:5 row_mask:0xf bank_mask:0xf
	v_fmac_f32_dpp v244, v242, v41 row_newbcast:6 row_mask:0xf bank_mask:0xf
	v_fmac_f32_dpp v245, v242, v42 row_newbcast:7 row_mask:0xf bank_mask:0xf
	v_fmac_f32_dpp v91, v242, v43 row_newbcast:8 row_mask:0xf bank_mask:0xf
	v_fmac_f32_dpp v243, v242, v44 row_newbcast:9 row_mask:0xf bank_mask:0xf
	v_fmac_f32_dpp v244, v242, v45 row_newbcast:10 row_mask:0xf bank_mask:0xf
	v_fmac_f32_dpp v245, v242, v46 row_newbcast:11 row_mask:0xf bank_mask:0xf
	v_fmac_f32_dpp v91, v242, v47 row_newbcast:12 row_mask:0xf bank_mask:0xf
	v_fmac_f32_dpp v243, v242, v48 row_newbcast:13 row_mask:0xf bank_mask:0xf
	v_fmac_f32_dpp v244, v242, v49 row_newbcast:14 row_mask:0xf bank_mask:0xf
	v_add_f32_e32 v91, v91, v243
	v_add_f32_e32 v244, v244, v245
	v_add_f32_e32 v91, v91, v244
	s_nop 1
	v_permlane32_swap_b32_e32 v35, v37
	v_permlane32_swap_b32_e32 v36, v38
	v_permlane32_swap_b32_e32 v39, v41
	v_permlane32_swap_b32_e32 v40, v42
	v_permlane32_swap_b32_e32 v43, v45
	v_permlane32_swap_b32_e32 v44, v46
	v_permlane32_swap_b32_e32 v47, v49
	v_permlane32_swap_b32_e32 v48, v91
	v_permlane16_swap_b32_e32 v35, v36
	v_permlane16_swap_b32_e32 v37, v38
	v_permlane16_swap_b32_e32 v39, v40
	v_permlane16_swap_b32_e32 v41, v42
	v_permlane16_swap_b32_e32 v43, v44
	v_permlane16_swap_b32_e32 v45, v46
	v_permlane16_swap_b32_e32 v47, v48
	v_permlane16_swap_b32_e32 v49, v91
	s_nop 1
	ds_read_u16 v92, v232 offset:4608
	ds_read_u16 v93, v232 offset:4752
	ds_read_u16 v94, v232 offset:4896
	ds_read_u16 v95, v232 offset:5040
	ds_read_u16 v96, v232 offset:5184
	ds_read_u16 v97, v232 offset:5328
	ds_read_u16 v98, v232 offset:5472
	ds_read_u16 v99, v232 offset:5616
	ds_read_b32 v234, v229 offset:8704
	ds_read_b32 v235, v229 offset:8720
	ds_read_b32 v242, v229 offset:8736
	ds_read_b32 v243, v229 offset:8752
	s_waitcnt lgkmcnt(3)
	v_mfma_f32_16x16x4_f32 v[204:207], v234, v18, 0
	v_mfma_f32_16x16x4_f32 v[208:211], v234, v19, 0
	v_mfma_f32_16x16x4_f32 v[212:215], v234, v20, 0
	v_mfma_f32_16x16x4_f32 v[222:225], v234, v21, 0
	ds_read_b32 v244, v229 offset:8768
	s_waitcnt lgkmcnt(3)
	v_mfma_f32_16x16x4_f32 v[204:207], v235, v22, v[204:207]
	v_mfma_f32_16x16x4_f32 v[208:211], v235, v24, v[208:211]
	v_mfma_f32_16x16x4_f32 v[212:215], v235, v25, v[212:215]
	v_mfma_f32_16x16x4_f32 v[222:225], v235, v26, v[222:225]
	ds_read_b32 v245, v229 offset:8784
	s_waitcnt lgkmcnt(3)
	v_mfma_f32_16x16x4_f32 v[204:207], v242, v27, v[204:207]
	v_mfma_f32_16x16x4_f32 v[208:211], v242, v28, v[208:211]
	v_mfma_f32_16x16x4_f32 v[212:215], v242, v29, v[212:215]
	v_mfma_f32_16x16x4_f32 v[222:225], v242, v30, v[222:225]
	ds_read_b32 v234, v229 offset:8800
	s_waitcnt lgkmcnt(3)
	v_mfma_f32_16x16x4_f32 v[204:207], v243, v31, v[204:207]
	v_mfma_f32_16x16x4_f32 v[208:211], v243, v32, v[208:211]
	v_mfma_f32_16x16x4_f32 v[212:215], v243, v33, v[212:215]
	v_mfma_f32_16x16x4_f32 v[222:225], v243, v34, v[222:225]
	ds_read_b32 v235, v229 offset:8816
	s_waitcnt lgkmcnt(3)
	v_mfma_f32_16x16x4_f32 v[204:207], v244, v35, v[204:207]
	v_mfma_f32_16x16x4_f32 v[208:211], v244, v36, v[208:211]
	v_mfma_f32_16x16x4_f32 v[212:215], v244, v37, v[212:215]
	v_mfma_f32_16x16x4_f32 v[222:225], v244, v38, v[222:225]
	s_waitcnt lgkmcnt(2)
	v_mfma_f32_16x16x4_f32 v[204:207], v245, v39, v[204:207]
	v_mfma_f32_16x16x4_f32 v[208:211], v245, v40, v[208:211]
	v_mfma_f32_16x16x4_f32 v[212:215], v245, v41, v[212:215]
	v_mfma_f32_16x16x4_f32 v[222:225], v245, v42, v[222:225]
	s_waitcnt lgkmcnt(1)
	v_mfma_f32_16x16x4_f32 v[204:207], v234, v43, v[204:207]
	v_mfma_f32_16x16x4_f32 v[208:211], v234, v44, v[208:211]
	v_mfma_f32_16x16x4_f32 v[212:215], v234, v45, v[212:215]
	v_mfma_f32_16x16x4_f32 v[222:225], v234, v46, v[222:225]
	s_waitcnt lgkmcnt(0)
	v_mfma_f32_16x16x4_f32 v[204:207], v235, v47, v[204:207]
	v_mfma_f32_16x16x4_f32 v[208:211], v235, v48, v[208:211]
	v_mfma_f32_16x16x4_f32 v[212:215], v235, v49, v[212:215]
	v_mfma_f32_16x16x4_f32 v[222:225], v235, v91, v[222:225]
	ds_read_u16 v100, v232 offset:5760
	ds_read_u16 v101, v232 offset:5904
	ds_read_u16 v102, v232 offset:6048
	ds_read_u16 v103, v232 offset:6192
	ds_read_u16 v104, v232 offset:6336
	ds_read_u16 v105, v232 offset:6480
	ds_read_u16 v185, v232 offset:6624
	ds_read_u16 v186, v232 offset:6768
	s_waitcnt lgkmcnt(0)
	v_lshlrev_b32_e32 v92, 16, v92
	v_lshlrev_b32_e32 v93, 16, v93
	v_lshlrev_b32_e32 v94, 16, v94
	v_lshlrev_b32_e32 v95, 16, v95
	v_lshlrev_b32_e32 v96, 16, v96
	v_lshlrev_b32_e32 v97, 16, v97
	v_lshlrev_b32_e32 v98, 16, v98
	v_lshlrev_b32_e32 v99, 16, v99
	v_lshlrev_b32_e32 v100, 16, v100
	v_lshlrev_b32_e32 v101, 16, v101
	v_lshlrev_b32_e32 v102, 16, v102
	v_lshlrev_b32_e32 v103, 16, v103
	v_lshlrev_b32_e32 v104, 16, v104
	v_lshlrev_b32_e32 v105, 16, v105
	v_lshlrev_b32_e32 v185, 16, v185
	v_lshlrev_b32_e32 v186, 16, v186
	s_nop 10
	s_nop 1
	v_permlane32_swap_b32_e32 v204, v212
	v_permlane32_swap_b32_e32 v208, v222
	v_permlane32_swap_b32_e32 v205, v213
	v_permlane32_swap_b32_e32 v209, v223
	v_permlane32_swap_b32_e32 v206, v214
	v_permlane32_swap_b32_e32 v210, v224
	v_permlane32_swap_b32_e32 v207, v215
	v_permlane32_swap_b32_e32 v211, v225
	v_permlane16_swap_b32_e32 v204, v208
	v_permlane16_swap_b32_e32 v212, v222
	v_permlane16_swap_b32_e32 v205, v209
	v_permlane16_swap_b32_e32 v213, v223
	v_permlane16_swap_b32_e32 v206, v210
	v_permlane16_swap_b32_e32 v214, v224
	v_permlane16_swap_b32_e32 v207, v211
	v_permlane16_swap_b32_e32 v215, v225
	s_nop 1
	v_add_f32_e32 v92, v92, v204
	v_add_f32_e32 v96, v96, v208
	v_add_f32_e32 v100, v100, v212
	v_add_f32_e32 v104, v104, v222
	v_add_f32_e32 v93, v93, v205
	v_add_f32_e32 v97, v97, v209
	v_add_f32_e32 v101, v101, v213
	v_add_f32_e32 v105, v105, v223
	v_add_f32_e32 v94, v94, v206
	v_add_f32_e32 v98, v98, v210
	v_add_f32_e32 v102, v102, v214
	v_add_f32_e32 v185, v185, v224
	v_add_f32_e32 v95, v95, v207
	v_add_f32_e32 v99, v99, v211
	v_add_f32_e32 v103, v103, v215
	v_add_f32_e32 v186, v186, v225
	ds_read_b32 v234, v228 offset:9104
	ds_read_b32 v235, v228 offset:9376
	ds_read_b32 v242, v228 offset:9648
	s_waitcnt lgkmcnt(2)
	v_fmac_f32_dpp v93, v234, v92 row_newbcast:0 row_mask:0xf bank_mask:0xf
	ds_read_b32 v234, v228 offset:9920
	s_waitcnt lgkmcnt(2)
	v_fmac_f32_dpp v94, v235, v92 row_newbcast:0 row_mask:0xf bank_mask:0xf
	v_mul_f32_dpp v243, v235, v93 row_newbcast:1 row_mask:0xf bank_mask:0xf
	v_add_f32_e32 v94, v94, v243
	ds_read_b32 v235, v228 offset:10192
	s_waitcnt lgkmcnt(2)
	v_fmac_f32_dpp v95, v242, v92 row_newbcast:0 row_mask:0xf bank_mask:0xf
	v_mul_f32_dpp v243, v242, v93 row_newbcast:1 row_mask:0xf bank_mask:0xf
	v_mul_f32_dpp v244, v242, v94 row_newbcast:2 row_mask:0xf bank_mask:0xf
	v_add_f32_e32 v95, v95, v243
	v_add_f32_e32 v95, v95, v244
	ds_read_b32 v242, v228 offset:10464
	s_waitcnt lgkmcnt(2)
	v_fmac_f32_dpp v96, v234, v92 row_newbcast:0 row_mask:0xf bank_mask:0xf
	v_mul_f32_dpp v243, v234, v93 row_newbcast:1 row_mask:0xf bank_mask:0xf
	v_mul_f32_dpp v244, v234, v94 row_newbcast:2 row_mask:0xf bank_mask:0xf
	v_mul_f32_dpp v245, v234, v95 row_newbcast:3 row_mask:0xf bank_mask:0xf
	v_add_f32_e32 v96, v96, v243
	v_add_f32_e32 v244, v244, v245
	v_add_f32_e32 v96, v96, v244
	ds_read_b32 v234, v228 offset:10736
	s_waitcnt lgkmcnt(2)
	v_fmac_f32_dpp v97, v235, v92 row_newbcast:0 row_mask:0xf bank_mask:0xf
	v_mul_f32_dpp v243, v235, v93 row_newbcast:1 row_mask:0xf bank_mask:0xf
	v_mul_f32_dpp v244, v235, v94 row_newbcast:2 row_mask:0xf bank_mask:0xf
	v_mul_f32_dpp v245, v235, v95 row_newbcast:3 row_mask:0xf bank_mask:0xf
	v_fmac_f32_dpp v97, v235, v96 row_newbcast:4 row_mask:0xf bank_mask:0xf
	v_add_f32_e32 v97, v97, v243
	v_add_f32_e32 v244, v244, v245
	v_add_f32_e32 v97, v97, v244
	ds_read_b32 v235, v228 offset:11008
	s_waitcnt lgkmcnt(2)
	v_fmac_f32_dpp v98, v242, v92 row_newbcast:0 row_mask:0xf bank_mask:0xf
	v_mul_f32_dpp v243, v242, v93 row_newbcast:1 row_mask:0xf bank_mask:0xf
	v_mul_f32_dpp v244, v242, v94 row_newbcast:2 row_mask:0xf bank_mask:0xf
	v_mul_f32_dpp v245, v242, v95 row_newbcast:3 row_mask:0xf bank_mask:0xf
	v_fmac_f32_dpp v98, v242, v96 row_newbcast:4 row_mask:0xf bank_mask:0xf
	v_fmac_f32_dpp v243, v242, v97 row_newbcast:5 row_mask:0xf bank_mask:0xf
	v_add_f32_e32 v98, v98, v243
	v_add_f32_e32 v244, v244, v245
	v_add_f32_e32 v98, v98, v244
	ds_read_b32 v242, v228 offset:11280
	s_waitcnt lgkmcnt(2)
	v_fmac_f32_dpp v99, v234, v92 row_newbcast:0 row_mask:0xf bank_mask:0xf
	v_mul_f32_dpp v243, v234, v93 row_newbcast:1 row_mask:0xf bank_mask:0xf
	v_mul_f32_dpp v244, v234, v94 row_newbcast:2 row_mask:0xf bank_mask:0xf
	v_mul_f32_dpp v245, v234, v95 row_newbcast:3 row_mask:0xf bank_mask:0xf
	v_fmac_f32_dpp v99, v234, v96 row_newbcast:4 row_mask:0xf bank_mask:0xf
	v_fmac_f32_dpp v243, v234, v97 row_newbcast:5 row_mask:0xf bank_mask:0xf
	v_fmac_f32_dpp v244, v234, v98 row_newbcast:6 row_mask:0xf bank_mask:0xf
	v_add_f32_e32 v99, v99, v243
	v_add_f32_e32 v244, v244, v245
	v_add_f32_e32 v99, v99, v244
	ds_read_b32 v234, v228 offset:11552
	s_waitcnt lgkmcnt(2)
	v_fmac_f32_dpp v100, v235, v92 row_newbcast:0 row_mask:0xf bank_mask:0xf
	v_mul_f32_dpp v243, v235, v93 row_newbcast:1 row_mask:0xf bank_mask:0xf
	v_mul_f32_dpp v244, v235, v94 row_newbcast:2 row_mask:0xf bank_mask:0xf
	v_mul_f32_dpp v245, v235, v95 row_newbcast:3 row_mask:0xf bank_mask:0xf
	v_fmac_f32_dpp v100, v235, v96 row_newbcast:4 row_mask:0xf bank_mask:0xf
	v_fmac_f32_dpp v243, v235, v97 row_newbcast:5 row_mask:0xf bank_mask:0xf
	v_fmac_f32_dpp v244, v235, v98 row_newbcast:6 row_mask:0xf bank_mask:0xf
	v_fmac_f32_dpp v245, v235, v99 row_newbcast:7 row_mask:0xf bank_mask:0xf
	v_add_f32_e32 v100, v100, v243
	v_add_f32_e32 v244, v244, v245
	v_add_f32_e32 v100, v100, v244
	ds_read_b32 v235, v228 offset:11824
	s_waitcnt lgkmcnt(2)
	v_fmac_f32_dpp v101, v242, v92 row_newbcast:0 row_mask:0xf bank_mask:0xf
	v_mul_f32_dpp v243, v242, v93 row_newbcast:1 row_mask:0xf bank_mask:0xf
	v_mul_f32_dpp v244, v242, v94 row_newbcast:2 row_mask:0xf bank_mask:0xf
	v_mul_f32_dpp v245, v242, v95 row_newbcast:3 row_mask:0xf bank_mask:0xf
	v_fmac_f32_dpp v101, v242, v96 row_newbcast:4 row_mask:0xf bank_mask:0xf
	v_fmac_f32_dpp v243, v242, v97 row_newbcast:5 row_mask:0xf bank_mask:0xf
	v_fmac_f32_dpp v244, v242, v98 row_newbcast:6 row_mask:0xf bank_mask:0xf
	v_fmac_f32_dpp v245, v242, v99 row_newbcast:7 row_mask:0xf bank_mask:0xf
	v_fmac_f32_dpp v101, v242, v100 row_newbcast:8 row_mask:0xf bank_mask:0xf
	v_add_f32_e32 v101, v101, v243
	v_add_f32_e32 v244, v244, v245
	v_add_f32_e32 v101, v101, v244
	ds_read_b32 v242, v228 offset:12096
	s_waitcnt lgkmcnt(2)
	v_fmac_f32_dpp v102, v234, v92 row_newbcast:0 row_mask:0xf bank_mask:0xf
	v_mul_f32_dpp v243, v234, v93 row_newbcast:1 row_mask:0xf bank_mask:0xf
	v_mul_f32_dpp v244, v234, v94 row_newbcast:2 row_mask:0xf bank_mask:0xf
	v_mul_f32_dpp v245, v234, v95 row_newbcast:3 row_mask:0xf bank_mask:0xf
	v_fmac_f32_dpp v102, v234, v96 row_newbcast:4 row_mask:0xf bank_mask:0xf
	v_fmac_f32_dpp v243, v234, v97 row_newbcast:5 row_mask:0xf bank_mask:0xf
	v_fmac_f32_dpp v244, v234, v98 row_newbcast:6 row_mask:0xf bank_mask:0xf
	v_fmac_f32_dpp v245, v234, v99 row_newbcast:7 row_mask:0xf bank_mask:0xf
	v_fmac_f32_dpp v102, v234, v100 row_newbcast:8 row_mask:0xf bank_mask:0xf
	v_fmac_f32_dpp v243, v234, v101 row_newbcast:9 row_mask:0xf bank_mask:0xf
	v_add_f32_e32 v102, v102, v243
	v_add_f32_e32 v244, v244, v245
	v_add_f32_e32 v102, v102, v244
	ds_read_b32 v234, v228 offset:12368
	s_waitcnt lgkmcnt(2)
	v_fmac_f32_dpp v103, v235, v92 row_newbcast:0 row_mask:0xf bank_mask:0xf
	v_mul_f32_dpp v243, v235, v93 row_newbcast:1 row_mask:0xf bank_mask:0xf
	v_mul_f32_dpp v244, v235, v94 row_newbcast:2 row_mask:0xf bank_mask:0xf
	v_mul_f32_dpp v245, v235, v95 row_newbcast:3 row_mask:0xf bank_mask:0xf
	v_fmac_f32_dpp v103, v235, v96 row_newbcast:4 row_mask:0xf bank_mask:0xf
	v_fmac_f32_dpp v243, v235, v97 row_newbcast:5 row_mask:0xf bank_mask:0xf
	v_fmac_f32_dpp v244, v235, v98 row_newbcast:6 row_mask:0xf bank_mask:0xf
	v_fmac_f32_dpp v245, v235, v99 row_newbcast:7 row_mask:0xf bank_mask:0xf
	v_fmac_f32_dpp v103, v235, v100 row_newbcast:8 row_mask:0xf bank_mask:0xf
	v_fmac_f32_dpp v243, v235, v101 row_newbcast:9 row_mask:0xf bank_mask:0xf
	v_fmac_f32_dpp v244, v235, v102 row_newbcast:10 row_mask:0xf bank_mask:0xf
	v_add_f32_e32 v103, v103, v243
	v_add_f32_e32 v244, v244, v245
	v_add_f32_e32 v103, v103, v244
	ds_read_b32 v235, v228 offset:12640
	s_waitcnt lgkmcnt(2)
	v_fmac_f32_dpp v104, v242, v92 row_newbcast:0 row_mask:0xf bank_mask:0xf
	v_mul_f32_dpp v243, v242, v93 row_newbcast:1 row_mask:0xf bank_mask:0xf
	v_mul_f32_dpp v244, v242, v94 row_newbcast:2 row_mask:0xf bank_mask:0xf
	v_mul_f32_dpp v245, v242, v95 row_newbcast:3 row_mask:0xf bank_mask:0xf
	v_fmac_f32_dpp v104, v242, v96 row_newbcast:4 row_mask:0xf bank_mask:0xf
	v_fmac_f32_dpp v243, v242, v97 row_newbcast:5 row_mask:0xf bank_mask:0xf
	v_fmac_f32_dpp v244, v242, v98 row_newbcast:6 row_mask:0xf bank_mask:0xf
	v_fmac_f32_dpp v245, v242, v99 row_newbcast:7 row_mask:0xf bank_mask:0xf
	v_fmac_f32_dpp v104, v242, v100 row_newbcast:8 row_mask:0xf bank_mask:0xf
	v_fmac_f32_dpp v243, v242, v101 row_newbcast:9 row_mask:0xf bank_mask:0xf
	v_fmac_f32_dpp v244, v242, v102 row_newbcast:10 row_mask:0xf bank_mask:0xf
	v_fmac_f32_dpp v245, v242, v103 row_newbcast:11 row_mask:0xf bank_mask:0xf
	v_add_f32_e32 v104, v104, v243
	v_add_f32_e32 v244, v244, v245
	v_add_f32_e32 v104, v104, v244
	ds_read_b32 v242, v228 offset:12912
	s_waitcnt lgkmcnt(2)
	v_fmac_f32_dpp v105, v234, v92 row_newbcast:0 row_mask:0xf bank_mask:0xf
	v_mul_f32_dpp v243, v234, v93 row_newbcast:1 row_mask:0xf bank_mask:0xf
	v_mul_f32_dpp v244, v234, v94 row_newbcast:2 row_mask:0xf bank_mask:0xf
	v_mul_f32_dpp v245, v234, v95 row_newbcast:3 row_mask:0xf bank_mask:0xf
	v_fmac_f32_dpp v105, v234, v96 row_newbcast:4 row_mask:0xf bank_mask:0xf
	v_fmac_f32_dpp v243, v234, v97 row_newbcast:5 row_mask:0xf bank_mask:0xf
	v_fmac_f32_dpp v244, v234, v98 row_newbcast:6 row_mask:0xf bank_mask:0xf
	v_fmac_f32_dpp v245, v234, v99 row_newbcast:7 row_mask:0xf bank_mask:0xf
	v_fmac_f32_dpp v105, v234, v100 row_newbcast:8 row_mask:0xf bank_mask:0xf
	v_fmac_f32_dpp v243, v234, v101 row_newbcast:9 row_mask:0xf bank_mask:0xf
	v_fmac_f32_dpp v244, v234, v102 row_newbcast:10 row_mask:0xf bank_mask:0xf
	v_fmac_f32_dpp v245, v234, v103 row_newbcast:11 row_mask:0xf bank_mask:0xf
	v_fmac_f32_dpp v105, v234, v104 row_newbcast:12 row_mask:0xf bank_mask:0xf
	v_add_f32_e32 v105, v105, v243
	v_add_f32_e32 v244, v244, v245
	v_add_f32_e32 v105, v105, v244
	s_waitcnt lgkmcnt(1)
	v_fmac_f32_dpp v185, v235, v92 row_newbcast:0 row_mask:0xf bank_mask:0xf
	v_mul_f32_dpp v243, v235, v93 row_newbcast:1 row_mask:0xf bank_mask:0xf
	v_mul_f32_dpp v244, v235, v94 row_newbcast:2 row_mask:0xf bank_mask:0xf
	v_mul_f32_dpp v245, v235, v95 row_newbcast:3 row_mask:0xf bank_mask:0xf
	v_fmac_f32_dpp v185, v235, v96 row_newbcast:4 row_mask:0xf bank_mask:0xf
	v_fmac_f32_dpp v243, v235, v97 row_newbcast:5 row_mask:0xf bank_mask:0xf
	v_fmac_f32_dpp v244, v235, v98 row_newbcast:6 row_mask:0xf bank_mask:0xf
	v_fmac_f32_dpp v245, v235, v99 row_newbcast:7 row_mask:0xf bank_mask:0xf
	v_fmac_f32_dpp v185, v235, v100 row_newbcast:8 row_mask:0xf bank_mask:0xf
	v_fmac_f32_dpp v243, v235, v101 row_newbcast:9 row_mask:0xf bank_mask:0xf
	v_fmac_f32_dpp v244, v235, v102 row_newbcast:10 row_mask:0xf bank_mask:0xf
	v_fmac_f32_dpp v245, v235, v103 row_newbcast:11 row_mask:0xf bank_mask:0xf
	v_fmac_f32_dpp v185, v235, v104 row_newbcast:12 row_mask:0xf bank_mask:0xf
	v_fmac_f32_dpp v243, v235, v105 row_newbcast:13 row_mask:0xf bank_mask:0xf
	v_add_f32_e32 v185, v185, v243
	v_add_f32_e32 v244, v244, v245
	v_add_f32_e32 v185, v185, v244
	s_waitcnt lgkmcnt(0)
	v_fmac_f32_dpp v186, v242, v92 row_newbcast:0 row_mask:0xf bank_mask:0xf
	v_mul_f32_dpp v243, v242, v93 row_newbcast:1 row_mask:0xf bank_mask:0xf
	v_mul_f32_dpp v244, v242, v94 row_newbcast:2 row_mask:0xf bank_mask:0xf
	v_mul_f32_dpp v245, v242, v95 row_newbcast:3 row_mask:0xf bank_mask:0xf
	v_fmac_f32_dpp v186, v242, v96 row_newbcast:4 row_mask:0xf bank_mask:0xf
	v_fmac_f32_dpp v243, v242, v97 row_newbcast:5 row_mask:0xf bank_mask:0xf
	v_fmac_f32_dpp v244, v242, v98 row_newbcast:6 row_mask:0xf bank_mask:0xf
	v_fmac_f32_dpp v245, v242, v99 row_newbcast:7 row_mask:0xf bank_mask:0xf
	v_fmac_f32_dpp v186, v242, v100 row_newbcast:8 row_mask:0xf bank_mask:0xf
	v_fmac_f32_dpp v243, v242, v101 row_newbcast:9 row_mask:0xf bank_mask:0xf
	v_fmac_f32_dpp v244, v242, v102 row_newbcast:10 row_mask:0xf bank_mask:0xf
	v_fmac_f32_dpp v245, v242, v103 row_newbcast:11 row_mask:0xf bank_mask:0xf
	v_fmac_f32_dpp v186, v242, v104 row_newbcast:12 row_mask:0xf bank_mask:0xf
	v_fmac_f32_dpp v243, v242, v105 row_newbcast:13 row_mask:0xf bank_mask:0xf
	v_fmac_f32_dpp v244, v242, v185 row_newbcast:14 row_mask:0xf bank_mask:0xf
	v_add_f32_e32 v186, v186, v243
	v_add_f32_e32 v244, v244, v245
	v_add_f32_e32 v186, v186, v244
	s_nop 1
	v_permlane32_swap_b32_e32 v92, v94
	v_permlane32_swap_b32_e32 v93, v95
	v_permlane32_swap_b32_e32 v96, v98
	v_permlane32_swap_b32_e32 v97, v99
	v_permlane32_swap_b32_e32 v100, v102
	v_permlane32_swap_b32_e32 v101, v103
	v_permlane32_swap_b32_e32 v104, v185
	v_permlane32_swap_b32_e32 v105, v186
	v_permlane16_swap_b32_e32 v92, v93
	v_permlane16_swap_b32_e32 v94, v95
	v_permlane16_swap_b32_e32 v96, v97
	v_permlane16_swap_b32_e32 v98, v99
	v_permlane16_swap_b32_e32 v100, v101
	v_permlane16_swap_b32_e32 v102, v103
	v_permlane16_swap_b32_e32 v104, v105
	v_permlane16_swap_b32_e32 v185, v186
	s_nop 1
	ds_read_u16 v187, v232 offset:6912
	ds_read_u16 v188, v232 offset:7056
	ds_read_u16 v189, v232 offset:7200
	ds_read_u16 v190, v232 offset:7344
	ds_read_u16 v192, v232 offset:7488
	ds_read_u16 v193, v232 offset:7632
	ds_read_u16 v194, v232 offset:7776
	ds_read_u16 v195, v232 offset:7920
	ds_read_b32 v234, v229 offset:13056
	ds_read_b32 v235, v229 offset:13072
	ds_read_b32 v242, v229 offset:13088
	ds_read_b32 v243, v229 offset:13104
	s_waitcnt lgkmcnt(3)
	v_mfma_f32_16x16x4_f32 v[204:207], v234, v18, 0
	v_mfma_f32_16x16x4_f32 v[208:211], v234, v19, 0
	v_mfma_f32_16x16x4_f32 v[212:215], v234, v20, 0
	v_mfma_f32_16x16x4_f32 v[222:225], v234, v21, 0
	ds_read_b32 v244, v229 offset:13120
	s_waitcnt lgkmcnt(3)
	v_mfma_f32_16x16x4_f32 v[204:207], v235, v22, v[204:207]
	v_mfma_f32_16x16x4_f32 v[208:211], v235, v24, v[208:211]
	v_mfma_f32_16x16x4_f32 v[212:215], v235, v25, v[212:215]
	v_mfma_f32_16x16x4_f32 v[222:225], v235, v26, v[222:225]
	ds_read_b32 v245, v229 offset:13136
	s_waitcnt lgkmcnt(3)
	v_mfma_f32_16x16x4_f32 v[204:207], v242, v27, v[204:207]
	v_mfma_f32_16x16x4_f32 v[208:211], v242, v28, v[208:211]
	v_mfma_f32_16x16x4_f32 v[212:215], v242, v29, v[212:215]
	v_mfma_f32_16x16x4_f32 v[222:225], v242, v30, v[222:225]
	ds_read_b32 v234, v229 offset:13152
	s_waitcnt lgkmcnt(3)
	v_mfma_f32_16x16x4_f32 v[204:207], v243, v31, v[204:207]
	v_mfma_f32_16x16x4_f32 v[208:211], v243, v32, v[208:211]
	v_mfma_f32_16x16x4_f32 v[212:215], v243, v33, v[212:215]
	v_mfma_f32_16x16x4_f32 v[222:225], v243, v34, v[222:225]
	ds_read_b32 v235, v229 offset:13168
	s_waitcnt lgkmcnt(3)
	v_mfma_f32_16x16x4_f32 v[204:207], v244, v35, v[204:207]
	v_mfma_f32_16x16x4_f32 v[208:211], v244, v36, v[208:211]
	v_mfma_f32_16x16x4_f32 v[212:215], v244, v37, v[212:215]
	v_mfma_f32_16x16x4_f32 v[222:225], v244, v38, v[222:225]
	ds_read_b32 v242, v229 offset:13184
	s_waitcnt lgkmcnt(3)
	v_mfma_f32_16x16x4_f32 v[204:207], v245, v39, v[204:207]
	v_mfma_f32_16x16x4_f32 v[208:211], v245, v40, v[208:211]
	v_mfma_f32_16x16x4_f32 v[212:215], v245, v41, v[212:215]
	v_mfma_f32_16x16x4_f32 v[222:225], v245, v42, v[222:225]
	ds_read_b32 v243, v229 offset:13200
	s_waitcnt lgkmcnt(3)
	v_mfma_f32_16x16x4_f32 v[204:207], v234, v43, v[204:207]
	v_mfma_f32_16x16x4_f32 v[208:211], v234, v44, v[208:211]
	v_mfma_f32_16x16x4_f32 v[212:215], v234, v45, v[212:215]
	v_mfma_f32_16x16x4_f32 v[222:225], v234, v46, v[222:225]
	ds_read_b32 v244, v229 offset:13216
	s_waitcnt lgkmcnt(3)
	v_mfma_f32_16x16x4_f32 v[204:207], v235, v47, v[204:207]
	v_mfma_f32_16x16x4_f32 v[208:211], v235, v48, v[208:211]
	v_mfma_f32_16x16x4_f32 v[212:215], v235, v49, v[212:215]
	v_mfma_f32_16x16x4_f32 v[222:225], v235, v91, v[222:225]
	ds_read_b32 v245, v229 offset:13232
	s_waitcnt lgkmcnt(3)
	v_mfma_f32_16x16x4_f32 v[204:207], v242, v92, v[204:207]
	v_mfma_f32_16x16x4_f32 v[208:211], v242, v93, v[208:211]
	v_mfma_f32_16x16x4_f32 v[212:215], v242, v94, v[212:215]
	v_mfma_f32_16x16x4_f32 v[222:225], v242, v95, v[222:225]
	s_waitcnt lgkmcnt(2)
	v_mfma_f32_16x16x4_f32 v[204:207], v243, v96, v[204:207]
	v_mfma_f32_16x16x4_f32 v[208:211], v243, v97, v[208:211]
	v_mfma_f32_16x16x4_f32 v[212:215], v243, v98, v[212:215]
	v_mfma_f32_16x16x4_f32 v[222:225], v243, v99, v[222:225]
	s_waitcnt lgkmcnt(1)
	v_mfma_f32_16x16x4_f32 v[204:207], v244, v100, v[204:207]
	v_mfma_f32_16x16x4_f32 v[208:211], v244, v101, v[208:211]
	v_mfma_f32_16x16x4_f32 v[212:215], v244, v102, v[212:215]
	v_mfma_f32_16x16x4_f32 v[222:225], v244, v103, v[222:225]
	s_waitcnt lgkmcnt(0)
	v_mfma_f32_16x16x4_f32 v[204:207], v245, v104, v[204:207]
	v_mfma_f32_16x16x4_f32 v[208:211], v245, v105, v[208:211]
	v_mfma_f32_16x16x4_f32 v[212:215], v245, v185, v[212:215]
	v_mfma_f32_16x16x4_f32 v[222:225], v245, v186, v[222:225]
	ds_read_u16 v196, v232 offset:8064
	ds_read_u16 v197, v232 offset:8208
	ds_read_u16 v198, v232 offset:8352
	ds_read_u16 v199, v232 offset:8496
	ds_read_u16 v200, v232 offset:8640
	ds_read_u16 v201, v232 offset:8784
	ds_read_u16 v202, v232 offset:8928
	ds_read_u16 v203, v232 offset:9072
	s_waitcnt lgkmcnt(0)
	v_lshlrev_b32_e32 v187, 16, v187
	v_lshlrev_b32_e32 v188, 16, v188
	v_lshlrev_b32_e32 v189, 16, v189
	v_lshlrev_b32_e32 v190, 16, v190
	v_lshlrev_b32_e32 v192, 16, v192
	v_lshlrev_b32_e32 v193, 16, v193
	v_lshlrev_b32_e32 v194, 16, v194
	v_lshlrev_b32_e32 v195, 16, v195
	v_lshlrev_b32_e32 v196, 16, v196
	v_lshlrev_b32_e32 v197, 16, v197
	v_lshlrev_b32_e32 v198, 16, v198
	v_lshlrev_b32_e32 v199, 16, v199
	v_lshlrev_b32_e32 v200, 16, v200
	v_lshlrev_b32_e32 v201, 16, v201
	v_lshlrev_b32_e32 v202, 16, v202
	v_lshlrev_b32_e32 v203, 16, v203
	s_nop 10
	s_nop 1
	v_permlane32_swap_b32_e32 v204, v212
	v_permlane32_swap_b32_e32 v208, v222
	v_permlane32_swap_b32_e32 v205, v213
	v_permlane32_swap_b32_e32 v209, v223
	v_permlane32_swap_b32_e32 v206, v214
	v_permlane32_swap_b32_e32 v210, v224
	v_permlane32_swap_b32_e32 v207, v215
	v_permlane32_swap_b32_e32 v211, v225
	v_permlane16_swap_b32_e32 v204, v208
	v_permlane16_swap_b32_e32 v212, v222
	v_permlane16_swap_b32_e32 v205, v209
	v_permlane16_swap_b32_e32 v213, v223
	v_permlane16_swap_b32_e32 v206, v210
	v_permlane16_swap_b32_e32 v214, v224
	v_permlane16_swap_b32_e32 v207, v211
	v_permlane16_swap_b32_e32 v215, v225
	s_nop 1
	v_add_f32_e32 v187, v187, v204
	v_add_f32_e32 v192, v192, v208
	v_add_f32_e32 v196, v196, v212
	v_add_f32_e32 v200, v200, v222
	v_add_f32_e32 v188, v188, v205
	v_add_f32_e32 v193, v193, v209
	v_add_f32_e32 v197, v197, v213
	v_add_f32_e32 v201, v201, v223
	v_add_f32_e32 v189, v189, v206
	v_add_f32_e32 v194, v194, v210
	v_add_f32_e32 v198, v198, v214
	v_add_f32_e32 v202, v202, v224
	v_add_f32_e32 v190, v190, v207
	v_add_f32_e32 v195, v195, v211
	v_add_f32_e32 v199, v199, v215
	v_add_f32_e32 v203, v203, v225
	ds_read_b32 v234, v228 offset:13520
	ds_read_b32 v235, v228 offset:13792
	ds_read_b32 v242, v228 offset:14064
	s_waitcnt lgkmcnt(2)
	v_fmac_f32_dpp v188, v234, v187 row_newbcast:0 row_mask:0xf bank_mask:0xf
	ds_read_b32 v234, v228 offset:14336
	s_waitcnt lgkmcnt(2)
	v_fmac_f32_dpp v189, v235, v187 row_newbcast:0 row_mask:0xf bank_mask:0xf
	v_mul_f32_dpp v243, v235, v188 row_newbcast:1 row_mask:0xf bank_mask:0xf
	v_add_f32_e32 v189, v189, v243
	ds_read_b32 v235, v228 offset:14608
	s_waitcnt lgkmcnt(2)
	v_fmac_f32_dpp v190, v242, v187 row_newbcast:0 row_mask:0xf bank_mask:0xf
	v_mul_f32_dpp v243, v242, v188 row_newbcast:1 row_mask:0xf bank_mask:0xf
	v_mul_f32_dpp v244, v242, v189 row_newbcast:2 row_mask:0xf bank_mask:0xf
	v_add_f32_e32 v190, v190, v243
	v_add_f32_e32 v190, v190, v244
	ds_read_b32 v242, v228 offset:14880
	s_waitcnt lgkmcnt(2)
	v_fmac_f32_dpp v192, v234, v187 row_newbcast:0 row_mask:0xf bank_mask:0xf
	v_mul_f32_dpp v243, v234, v188 row_newbcast:1 row_mask:0xf bank_mask:0xf
	v_mul_f32_dpp v244, v234, v189 row_newbcast:2 row_mask:0xf bank_mask:0xf
	v_mul_f32_dpp v245, v234, v190 row_newbcast:3 row_mask:0xf bank_mask:0xf
	v_add_f32_e32 v192, v192, v243
	v_add_f32_e32 v244, v244, v245
	v_add_f32_e32 v192, v192, v244
	ds_read_b32 v234, v228 offset:15152
	s_waitcnt lgkmcnt(2)
	v_fmac_f32_dpp v193, v235, v187 row_newbcast:0 row_mask:0xf bank_mask:0xf
	v_mul_f32_dpp v243, v235, v188 row_newbcast:1 row_mask:0xf bank_mask:0xf
	v_mul_f32_dpp v244, v235, v189 row_newbcast:2 row_mask:0xf bank_mask:0xf
	v_mul_f32_dpp v245, v235, v190 row_newbcast:3 row_mask:0xf bank_mask:0xf
	v_fmac_f32_dpp v193, v235, v192 row_newbcast:4 row_mask:0xf bank_mask:0xf
	v_add_f32_e32 v193, v193, v243
	v_add_f32_e32 v244, v244, v245
	v_add_f32_e32 v193, v193, v244
	ds_read_b32 v235, v228 offset:15424
	s_waitcnt lgkmcnt(2)
	v_fmac_f32_dpp v194, v242, v187 row_newbcast:0 row_mask:0xf bank_mask:0xf
	v_mul_f32_dpp v243, v242, v188 row_newbcast:1 row_mask:0xf bank_mask:0xf
	v_mul_f32_dpp v244, v242, v189 row_newbcast:2 row_mask:0xf bank_mask:0xf
	v_mul_f32_dpp v245, v242, v190 row_newbcast:3 row_mask:0xf bank_mask:0xf
	v_fmac_f32_dpp v194, v242, v192 row_newbcast:4 row_mask:0xf bank_mask:0xf
	v_fmac_f32_dpp v243, v242, v193 row_newbcast:5 row_mask:0xf bank_mask:0xf
	v_add_f32_e32 v194, v194, v243
	v_add_f32_e32 v244, v244, v245
	v_add_f32_e32 v194, v194, v244
	ds_read_b32 v242, v228 offset:15696
	s_waitcnt lgkmcnt(2)
	v_fmac_f32_dpp v195, v234, v187 row_newbcast:0 row_mask:0xf bank_mask:0xf
	v_mul_f32_dpp v243, v234, v188 row_newbcast:1 row_mask:0xf bank_mask:0xf
	v_mul_f32_dpp v244, v234, v189 row_newbcast:2 row_mask:0xf bank_mask:0xf
	v_mul_f32_dpp v245, v234, v190 row_newbcast:3 row_mask:0xf bank_mask:0xf
	v_fmac_f32_dpp v195, v234, v192 row_newbcast:4 row_mask:0xf bank_mask:0xf
	v_fmac_f32_dpp v243, v234, v193 row_newbcast:5 row_mask:0xf bank_mask:0xf
	v_fmac_f32_dpp v244, v234, v194 row_newbcast:6 row_mask:0xf bank_mask:0xf
	v_add_f32_e32 v195, v195, v243
	v_add_f32_e32 v244, v244, v245
	v_add_f32_e32 v195, v195, v244
	ds_read_b32 v234, v228 offset:15968
	s_waitcnt lgkmcnt(2)
	v_fmac_f32_dpp v196, v235, v187 row_newbcast:0 row_mask:0xf bank_mask:0xf
	v_mul_f32_dpp v243, v235, v188 row_newbcast:1 row_mask:0xf bank_mask:0xf
	v_mul_f32_dpp v244, v235, v189 row_newbcast:2 row_mask:0xf bank_mask:0xf
	v_mul_f32_dpp v245, v235, v190 row_newbcast:3 row_mask:0xf bank_mask:0xf
	v_fmac_f32_dpp v196, v235, v192 row_newbcast:4 row_mask:0xf bank_mask:0xf
	v_fmac_f32_dpp v243, v235, v193 row_newbcast:5 row_mask:0xf bank_mask:0xf
	v_fmac_f32_dpp v244, v235, v194 row_newbcast:6 row_mask:0xf bank_mask:0xf
	v_fmac_f32_dpp v245, v235, v195 row_newbcast:7 row_mask:0xf bank_mask:0xf
	v_add_f32_e32 v196, v196, v243
	v_add_f32_e32 v244, v244, v245
	v_add_f32_e32 v196, v196, v244
	ds_read_b32 v235, v228 offset:16240
	s_waitcnt lgkmcnt(2)
	v_fmac_f32_dpp v197, v242, v187 row_newbcast:0 row_mask:0xf bank_mask:0xf
	v_mul_f32_dpp v243, v242, v188 row_newbcast:1 row_mask:0xf bank_mask:0xf
	v_mul_f32_dpp v244, v242, v189 row_newbcast:2 row_mask:0xf bank_mask:0xf
	v_mul_f32_dpp v245, v242, v190 row_newbcast:3 row_mask:0xf bank_mask:0xf
	v_fmac_f32_dpp v197, v242, v192 row_newbcast:4 row_mask:0xf bank_mask:0xf
	v_fmac_f32_dpp v243, v242, v193 row_newbcast:5 row_mask:0xf bank_mask:0xf
	v_fmac_f32_dpp v244, v242, v194 row_newbcast:6 row_mask:0xf bank_mask:0xf
	v_fmac_f32_dpp v245, v242, v195 row_newbcast:7 row_mask:0xf bank_mask:0xf
	v_fmac_f32_dpp v197, v242, v196 row_newbcast:8 row_mask:0xf bank_mask:0xf
	v_add_f32_e32 v197, v197, v243
	v_add_f32_e32 v244, v244, v245
	v_add_f32_e32 v197, v197, v244
	ds_read_b32 v242, v228 offset:16512
	s_waitcnt lgkmcnt(2)
	v_fmac_f32_dpp v198, v234, v187 row_newbcast:0 row_mask:0xf bank_mask:0xf
	v_mul_f32_dpp v243, v234, v188 row_newbcast:1 row_mask:0xf bank_mask:0xf
	v_mul_f32_dpp v244, v234, v189 row_newbcast:2 row_mask:0xf bank_mask:0xf
	v_mul_f32_dpp v245, v234, v190 row_newbcast:3 row_mask:0xf bank_mask:0xf
	v_fmac_f32_dpp v198, v234, v192 row_newbcast:4 row_mask:0xf bank_mask:0xf
	v_fmac_f32_dpp v243, v234, v193 row_newbcast:5 row_mask:0xf bank_mask:0xf
	v_fmac_f32_dpp v244, v234, v194 row_newbcast:6 row_mask:0xf bank_mask:0xf
	v_fmac_f32_dpp v245, v234, v195 row_newbcast:7 row_mask:0xf bank_mask:0xf
	v_fmac_f32_dpp v198, v234, v196 row_newbcast:8 row_mask:0xf bank_mask:0xf
	v_fmac_f32_dpp v243, v234, v197 row_newbcast:9 row_mask:0xf bank_mask:0xf
	v_add_f32_e32 v198, v198, v243
	v_add_f32_e32 v244, v244, v245
	v_add_f32_e32 v198, v198, v244
	ds_read_b32 v234, v228 offset:16784
	s_waitcnt lgkmcnt(2)
	v_fmac_f32_dpp v199, v235, v187 row_newbcast:0 row_mask:0xf bank_mask:0xf
	v_mul_f32_dpp v243, v235, v188 row_newbcast:1 row_mask:0xf bank_mask:0xf
	v_mul_f32_dpp v244, v235, v189 row_newbcast:2 row_mask:0xf bank_mask:0xf
	v_mul_f32_dpp v245, v235, v190 row_newbcast:3 row_mask:0xf bank_mask:0xf
	v_fmac_f32_dpp v199, v235, v192 row_newbcast:4 row_mask:0xf bank_mask:0xf
	v_fmac_f32_dpp v243, v235, v193 row_newbcast:5 row_mask:0xf bank_mask:0xf
	v_fmac_f32_dpp v244, v235, v194 row_newbcast:6 row_mask:0xf bank_mask:0xf
	v_fmac_f32_dpp v245, v235, v195 row_newbcast:7 row_mask:0xf bank_mask:0xf
	v_fmac_f32_dpp v199, v235, v196 row_newbcast:8 row_mask:0xf bank_mask:0xf
	v_fmac_f32_dpp v243, v235, v197 row_newbcast:9 row_mask:0xf bank_mask:0xf
	v_fmac_f32_dpp v244, v235, v198 row_newbcast:10 row_mask:0xf bank_mask:0xf
	v_add_f32_e32 v199, v199, v243
	v_add_f32_e32 v244, v244, v245
	v_add_f32_e32 v199, v199, v244
	ds_read_b32 v235, v228 offset:17056
	s_waitcnt lgkmcnt(2)
	v_fmac_f32_dpp v200, v242, v187 row_newbcast:0 row_mask:0xf bank_mask:0xf
	v_mul_f32_dpp v243, v242, v188 row_newbcast:1 row_mask:0xf bank_mask:0xf
	v_mul_f32_dpp v244, v242, v189 row_newbcast:2 row_mask:0xf bank_mask:0xf
	v_mul_f32_dpp v245, v242, v190 row_newbcast:3 row_mask:0xf bank_mask:0xf
	v_fmac_f32_dpp v200, v242, v192 row_newbcast:4 row_mask:0xf bank_mask:0xf
	v_fmac_f32_dpp v243, v242, v193 row_newbcast:5 row_mask:0xf bank_mask:0xf
	v_fmac_f32_dpp v244, v242, v194 row_newbcast:6 row_mask:0xf bank_mask:0xf
	v_fmac_f32_dpp v245, v242, v195 row_newbcast:7 row_mask:0xf bank_mask:0xf
	v_fmac_f32_dpp v200, v242, v196 row_newbcast:8 row_mask:0xf bank_mask:0xf
	v_fmac_f32_dpp v243, v242, v197 row_newbcast:9 row_mask:0xf bank_mask:0xf
	v_fmac_f32_dpp v244, v242, v198 row_newbcast:10 row_mask:0xf bank_mask:0xf
	v_fmac_f32_dpp v245, v242, v199 row_newbcast:11 row_mask:0xf bank_mask:0xf
	v_add_f32_e32 v200, v200, v243
	v_add_f32_e32 v244, v244, v245
	v_add_f32_e32 v200, v200, v244
	ds_read_b32 v242, v228 offset:17328
	s_waitcnt lgkmcnt(2)
	v_fmac_f32_dpp v201, v234, v187 row_newbcast:0 row_mask:0xf bank_mask:0xf
	v_mul_f32_dpp v243, v234, v188 row_newbcast:1 row_mask:0xf bank_mask:0xf
	v_mul_f32_dpp v244, v234, v189 row_newbcast:2 row_mask:0xf bank_mask:0xf
	v_mul_f32_dpp v245, v234, v190 row_newbcast:3 row_mask:0xf bank_mask:0xf
	v_fmac_f32_dpp v201, v234, v192 row_newbcast:4 row_mask:0xf bank_mask:0xf
	v_fmac_f32_dpp v243, v234, v193 row_newbcast:5 row_mask:0xf bank_mask:0xf
	v_fmac_f32_dpp v244, v234, v194 row_newbcast:6 row_mask:0xf bank_mask:0xf
	v_fmac_f32_dpp v245, v234, v195 row_newbcast:7 row_mask:0xf bank_mask:0xf
	v_fmac_f32_dpp v201, v234, v196 row_newbcast:8 row_mask:0xf bank_mask:0xf
	v_fmac_f32_dpp v243, v234, v197 row_newbcast:9 row_mask:0xf bank_mask:0xf
	v_fmac_f32_dpp v244, v234, v198 row_newbcast:10 row_mask:0xf bank_mask:0xf
	v_fmac_f32_dpp v245, v234, v199 row_newbcast:11 row_mask:0xf bank_mask:0xf
	v_fmac_f32_dpp v201, v234, v200 row_newbcast:12 row_mask:0xf bank_mask:0xf
	v_add_f32_e32 v201, v201, v243
	v_add_f32_e32 v244, v244, v245
	v_add_f32_e32 v201, v201, v244
	s_waitcnt lgkmcnt(1)
	v_fmac_f32_dpp v202, v235, v187 row_newbcast:0 row_mask:0xf bank_mask:0xf
	v_mul_f32_dpp v243, v235, v188 row_newbcast:1 row_mask:0xf bank_mask:0xf
	v_mul_f32_dpp v244, v235, v189 row_newbcast:2 row_mask:0xf bank_mask:0xf
	v_mul_f32_dpp v245, v235, v190 row_newbcast:3 row_mask:0xf bank_mask:0xf
	v_fmac_f32_dpp v202, v235, v192 row_newbcast:4 row_mask:0xf bank_mask:0xf
	v_fmac_f32_dpp v243, v235, v193 row_newbcast:5 row_mask:0xf bank_mask:0xf
	v_fmac_f32_dpp v244, v235, v194 row_newbcast:6 row_mask:0xf bank_mask:0xf
	v_fmac_f32_dpp v245, v235, v195 row_newbcast:7 row_mask:0xf bank_mask:0xf
	v_fmac_f32_dpp v202, v235, v196 row_newbcast:8 row_mask:0xf bank_mask:0xf
	v_fmac_f32_dpp v243, v235, v197 row_newbcast:9 row_mask:0xf bank_mask:0xf
	v_fmac_f32_dpp v244, v235, v198 row_newbcast:10 row_mask:0xf bank_mask:0xf
	v_fmac_f32_dpp v245, v235, v199 row_newbcast:11 row_mask:0xf bank_mask:0xf
	v_fmac_f32_dpp v202, v235, v200 row_newbcast:12 row_mask:0xf bank_mask:0xf
	v_fmac_f32_dpp v243, v235, v201 row_newbcast:13 row_mask:0xf bank_mask:0xf
	v_add_f32_e32 v202, v202, v243
	v_add_f32_e32 v244, v244, v245
	v_add_f32_e32 v202, v202, v244
	s_waitcnt lgkmcnt(0)
	v_fmac_f32_dpp v203, v242, v187 row_newbcast:0 row_mask:0xf bank_mask:0xf
	v_mul_f32_dpp v243, v242, v188 row_newbcast:1 row_mask:0xf bank_mask:0xf
	v_mul_f32_dpp v244, v242, v189 row_newbcast:2 row_mask:0xf bank_mask:0xf
	v_mul_f32_dpp v245, v242, v190 row_newbcast:3 row_mask:0xf bank_mask:0xf
	v_fmac_f32_dpp v203, v242, v192 row_newbcast:4 row_mask:0xf bank_mask:0xf
	v_fmac_f32_dpp v243, v242, v193 row_newbcast:5 row_mask:0xf bank_mask:0xf
	v_fmac_f32_dpp v244, v242, v194 row_newbcast:6 row_mask:0xf bank_mask:0xf
	v_fmac_f32_dpp v245, v242, v195 row_newbcast:7 row_mask:0xf bank_mask:0xf
	v_fmac_f32_dpp v203, v242, v196 row_newbcast:8 row_mask:0xf bank_mask:0xf
	v_fmac_f32_dpp v243, v242, v197 row_newbcast:9 row_mask:0xf bank_mask:0xf
	v_fmac_f32_dpp v244, v242, v198 row_newbcast:10 row_mask:0xf bank_mask:0xf
	v_fmac_f32_dpp v245, v242, v199 row_newbcast:11 row_mask:0xf bank_mask:0xf
	v_fmac_f32_dpp v203, v242, v200 row_newbcast:12 row_mask:0xf bank_mask:0xf
	v_fmac_f32_dpp v243, v242, v201 row_newbcast:13 row_mask:0xf bank_mask:0xf
	v_fmac_f32_dpp v244, v242, v202 row_newbcast:14 row_mask:0xf bank_mask:0xf
	v_add_f32_e32 v203, v203, v243
	v_add_f32_e32 v244, v244, v245
	v_add_f32_e32 v203, v203, v244
	s_nop 1
	v_permlane32_swap_b32_e32 v18, v20
	v_permlane32_swap_b32_e32 v19, v21
	v_permlane32_swap_b32_e32 v22, v25
	v_permlane32_swap_b32_e32 v24, v26
	v_permlane32_swap_b32_e32 v27, v29
	v_permlane32_swap_b32_e32 v28, v30
	v_permlane32_swap_b32_e32 v31, v33
	v_permlane32_swap_b32_e32 v32, v34
	v_permlane32_swap_b32_e32 v35, v37
	v_permlane32_swap_b32_e32 v36, v38
	v_permlane32_swap_b32_e32 v39, v41
	v_permlane32_swap_b32_e32 v40, v42
	v_permlane32_swap_b32_e32 v43, v45
	v_permlane32_swap_b32_e32 v44, v46
	v_permlane32_swap_b32_e32 v47, v49
	v_permlane32_swap_b32_e32 v48, v91
	v_permlane32_swap_b32_e32 v92, v94
	v_permlane32_swap_b32_e32 v93, v95
	v_permlane32_swap_b32_e32 v96, v98
	v_permlane32_swap_b32_e32 v97, v99
	v_permlane32_swap_b32_e32 v100, v102
	v_permlane32_swap_b32_e32 v101, v103
	v_permlane32_swap_b32_e32 v104, v185
	v_permlane32_swap_b32_e32 v105, v186
	v_permlane16_swap_b32_e32 v18, v19
	v_permlane16_swap_b32_e32 v20, v21
	v_permlane16_swap_b32_e32 v22, v24
	v_permlane16_swap_b32_e32 v25, v26
	v_permlane16_swap_b32_e32 v27, v28
	v_permlane16_swap_b32_e32 v29, v30
	v_permlane16_swap_b32_e32 v31, v32
	v_permlane16_swap_b32_e32 v33, v34
	v_permlane16_swap_b32_e32 v35, v36
	v_permlane16_swap_b32_e32 v37, v38
	v_permlane16_swap_b32_e32 v39, v40
	v_permlane16_swap_b32_e32 v41, v42
	v_permlane16_swap_b32_e32 v43, v44
	v_permlane16_swap_b32_e32 v45, v46
	v_permlane16_swap_b32_e32 v47, v48
	v_permlane16_swap_b32_e32 v49, v91
	v_permlane16_swap_b32_e32 v92, v93
	v_permlane16_swap_b32_e32 v94, v95
	v_permlane16_swap_b32_e32 v96, v97
	v_permlane16_swap_b32_e32 v98, v99
	v_permlane16_swap_b32_e32 v100, v101
	v_permlane16_swap_b32_e32 v102, v103
	v_permlane16_swap_b32_e32 v104, v105
	v_permlane16_swap_b32_e32 v185, v186
	s_nop 1
	s_barrier
	s_mov_b64 s[18:19], exec
	v_cvt_pk_bf16_f32 v204, v18, v19
	v_cvt_pk_bf16_f32 v205, v20, v21
	v_cvt_pk_bf16_f32 v206, v22, v24
	v_cvt_pk_bf16_f32 v207, v25, v26
	ds_write_b128 v233, v[204:207] offset:36864
	v_cvt_pk_bf16_f32 v204, v27, v28
	v_cvt_pk_bf16_f32 v205, v29, v30
	v_cvt_pk_bf16_f32 v206, v31, v32
	v_cvt_pk_bf16_f32 v207, v33, v34
	ds_write_b128 v233, v[204:207] offset:36880
	v_cvt_pk_bf16_f32 v204, v35, v36
	v_cvt_pk_bf16_f32 v205, v37, v38
	v_cvt_pk_bf16_f32 v206, v39, v40
	v_cvt_pk_bf16_f32 v207, v41, v42
	ds_write_b128 v233, v[204:207] offset:36896
	v_cvt_pk_bf16_f32 v204, v43, v44
	v_cvt_pk_bf16_f32 v205, v45, v46
	v_cvt_pk_bf16_f32 v206, v47, v48
	v_cvt_pk_bf16_f32 v207, v49, v91
	ds_write_b128 v233, v[204:207] offset:36912
	v_cvt_pk_bf16_f32 v204, v92, v93
	v_cvt_pk_bf16_f32 v205, v94, v95
	v_cvt_pk_bf16_f32 v206, v96, v97
	v_cvt_pk_bf16_f32 v207, v98, v99
	ds_write_b128 v233, v[204:207] offset:36928
	v_cvt_pk_bf16_f32 v204, v100, v101
	v_cvt_pk_bf16_f32 v205, v102, v103
	v_cvt_pk_bf16_f32 v206, v104, v105
	v_cvt_pk_bf16_f32 v207, v185, v186
	ds_write_b128 v233, v[204:207] offset:36944
	v_cvt_pk_bf16_f32 v204, v187, v188
	v_cvt_pk_bf16_f32 v205, v189, v190
	v_cvt_pk_bf16_f32 v206, v192, v193
	v_cvt_pk_bf16_f32 v207, v194, v195
	ds_write_b128 v233, v[204:207] offset:36960
	v_cvt_pk_bf16_f32 v204, v196, v197
	v_cvt_pk_bf16_f32 v205, v198, v199
	v_cvt_pk_bf16_f32 v206, v200, v201
	v_cvt_pk_bf16_f32 v207, v202, v203
	ds_write_b128 v233, v[204:207] offset:36976
	s_branch .LBB0_2333
